# added: GEMM K-loop back edge rotated so the loop-carried pointer/select block runs before the loop-back barrier
# baseline (speedup 1.0000x reference)
.Lrot_body_0:
	ds_read_b128 v[130:133], v157
	ds_read_b128 v[148:151], v157 offset:1024
	ds_read_b128 v[158:161], v157 offset:2048
	ds_read_b128 v[162:165], v157 offset:3072
	v_add_u32_e32 v157, s28, v153
	ds_read_b128 v[166:169], v157
	ds_read_b128 v[170:173], v157 offset:1024
	ds_read_b128 v[174:177], v157 offset:2048
	ds_read_b128 v[178:181], v157 offset:3072
	v_lshl_add_u64 v[192:193], s[30:31], 0, v[144:145]
	s_add_i32 m0, s75, 0xc000
	ds_read_b128 v[184:187], v156
	ds_read_b128 v[188:191], v156 offset:1024
	ds_read_b128 v[196:199], v156 offset:2048
	ds_read_b128 v[210:213], v156 offset:3072
	ds_read_b128 v[214:217], v156 offset:4096
	ds_read_b128 v[218:221], v156 offset:5120
	ds_read_b128 v[222:225], v156 offset:6144
	ds_read_b128 v[226:229], v156 offset:7168
	global_load_lds_dwordx4 v[192:193], off
	v_lshl_add_u64 v[192:193], s[30:31], 0, v[146:147]
	s_add_i32 m0, s75, 0xe000
	s_nop 0
	global_load_lds_dwordx4 v[192:193], off
	s_waitcnt vmcnt(8)
	s_waitcnt lgkmcnt(0)
	s_barrier
	s_setprio 1
	s_waitcnt lgkmcnt(0)
	v_mfma_f32_16x16x32_bf16 v[126:129], v[130:133], v[184:187], v[126:129]
	v_mfma_f32_16x16x32_bf16 v[122:125], v[158:161], v[184:187], v[122:125]
	v_mfma_f32_16x16x32_bf16 v[110:113], v[130:133], v[196:199], v[110:113]
	v_mfma_f32_16x16x32_bf16 v[106:109], v[158:161], v[196:199], v[106:109]
	v_mfma_f32_16x16x32_bf16 v[94:97], v[130:133], v[214:217], v[94:97]
	v_mfma_f32_16x16x32_bf16 v[90:93], v[158:161], v[214:217], v[90:93]
	v_mfma_f32_16x16x32_bf16 v[78:81], v[130:133], v[222:225], v[78:81]
	v_mfma_f32_16x16x32_bf16 v[74:77], v[158:161], v[222:225], v[74:77]
	v_mfma_f32_16x16x32_bf16 v[126:129], v[148:151], v[188:191], v[126:129]
	v_mfma_f32_16x16x32_bf16 v[122:125], v[162:165], v[188:191], v[122:125]
	v_mfma_f32_16x16x32_bf16 v[110:113], v[148:151], v[210:213], v[110:113]
	v_mfma_f32_16x16x32_bf16 v[106:109], v[162:165], v[210:213], v[106:109]
	v_mfma_f32_16x16x32_bf16 v[94:97], v[148:151], v[218:221], v[94:97]
	v_mfma_f32_16x16x32_bf16 v[90:93], v[162:165], v[218:221], v[90:93]
	v_mfma_f32_16x16x32_bf16 v[78:81], v[148:151], v[226:229], v[78:81]
	v_mfma_f32_16x16x32_bf16 v[74:77], v[162:165], v[226:229], v[74:77]
	s_setprio 0
	s_setprio 1
	v_mfma_f32_16x16x32_bf16 v[118:121], v[166:169], v[184:187], v[118:121]
	v_mfma_f32_16x16x32_bf16 v[114:117], v[174:177], v[184:187], v[114:117]
	v_mfma_f32_16x16x32_bf16 v[102:105], v[166:169], v[196:199], v[102:105]
	v_mfma_f32_16x16x32_bf16 v[98:101], v[174:177], v[196:199], v[98:101]
	v_mfma_f32_16x16x32_bf16 v[86:89], v[166:169], v[214:217], v[86:89]
	v_mfma_f32_16x16x32_bf16 v[82:85], v[174:177], v[214:217], v[82:85]
	v_mfma_f32_16x16x32_bf16 v[70:73], v[166:169], v[222:225], v[70:73]
	v_mfma_f32_16x16x32_bf16 v[66:69], v[174:177], v[222:225], v[66:69]
	v_mfma_f32_16x16x32_bf16 v[118:121], v[170:173], v[188:191], v[118:121]
	v_mfma_f32_16x16x32_bf16 v[114:117], v[178:181], v[188:191], v[114:117]
	v_mfma_f32_16x16x32_bf16 v[102:105], v[170:173], v[210:213], v[102:105]
	v_mfma_f32_16x16x32_bf16 v[98:101], v[178:181], v[210:213], v[98:101]
	v_mfma_f32_16x16x32_bf16 v[86:89], v[170:173], v[218:221], v[86:89]
	v_mfma_f32_16x16x32_bf16 v[82:85], v[178:181], v[218:221], v[82:85]
	v_mfma_f32_16x16x32_bf16 v[70:73], v[170:173], v[226:229], v[70:73]
	v_mfma_f32_16x16x32_bf16 v[66:69], v[178:181], v[226:229], v[66:69]
	s_setprio 0
	s_barrier
	s_add_i32 s43, s43, s17
	v_lshl_add_u64 v[192:193], s[36:37], 0, v[0:1]
	s_mov_b32 m0, s43
	ds_read_b128 v[184:187], v156 offset:16384
	ds_read_b128 v[188:191], v156 offset:17408
	ds_read_b128 v[196:199], v156 offset:18432
	ds_read_b128 v[210:213], v156 offset:19456
	ds_read_b128 v[214:217], v156 offset:20480
	ds_read_b128 v[218:221], v156 offset:21504
	ds_read_b128 v[222:225], v156 offset:22528
	ds_read_b128 v[226:229], v156 offset:23552
	global_load_lds_dwordx4 v[192:193], off
	s_add_i32 m0, s43, 0x2000
	s_add_u32 s70, s36, 0x40000
	v_lshl_add_u64 v[202:203], s[36:37], 0, v[134:135]
	s_addc_u32 s71, s37, 0
	s_add_i32 s28, s28, s17
	global_load_lds_dwordx4 v[202:203], off
	v_lshl_add_u64 v[230:231], s[70:71], 0, v[0:1]
	s_mov_b32 m0, s28
	v_lshl_add_u64 v[232:233], s[52:53], 0, v[136:137]
	global_load_lds_dwordx4 v[230:231], off
	v_lshl_add_u64 v[230:231], s[70:71], 0, v[134:135]
	s_add_i32 m0, s28, 0x2000
	s_nop 0
	global_load_lds_dwordx4 v[230:231], off
	v_lshl_add_u64 v[230:231], s[52:53], 0, v[138:139]
	s_mov_b32 m0, s75
	s_nop 0
	global_load_lds_dwordx4 v[230:231], off
	s_mov_b32 m0, s58
	s_nop 0
	global_load_lds_dwordx4 v[232:233], off
	s_waitcnt vmcnt(8)
	s_waitcnt lgkmcnt(0)
	s_barrier
	s_setprio 1
	s_waitcnt lgkmcnt(0)
	v_mfma_f32_16x16x32_bf16 v[62:65], v[130:133], v[184:187], v[62:65]
	v_mfma_f32_16x16x32_bf16 v[58:61], v[158:161], v[184:187], v[58:61]
	v_mfma_f32_16x16x32_bf16 v[46:49], v[130:133], v[196:199], v[46:49]
	v_mfma_f32_16x16x32_bf16 v[42:45], v[158:161], v[196:199], v[42:45]
	v_mfma_f32_16x16x32_bf16 v[30:33], v[130:133], v[214:217], v[30:33]
	v_mfma_f32_16x16x32_bf16 v[26:29], v[158:161], v[214:217], v[26:29]
	v_mfma_f32_16x16x32_bf16 v[14:17], v[130:133], v[222:225], v[14:17]
	v_mfma_f32_16x16x32_bf16 v[10:13], v[158:161], v[222:225], v[10:13]
	v_mfma_f32_16x16x32_bf16 v[62:65], v[148:151], v[188:191], v[62:65]
	v_mfma_f32_16x16x32_bf16 v[58:61], v[162:165], v[188:191], v[58:61]
	v_mfma_f32_16x16x32_bf16 v[46:49], v[148:151], v[210:213], v[46:49]
	v_mfma_f32_16x16x32_bf16 v[42:45], v[162:165], v[210:213], v[42:45]
	v_mfma_f32_16x16x32_bf16 v[30:33], v[148:151], v[218:221], v[30:33]
	v_mfma_f32_16x16x32_bf16 v[26:29], v[162:165], v[218:221], v[26:29]
	v_mfma_f32_16x16x32_bf16 v[14:17], v[148:151], v[226:229], v[14:17]
	v_mfma_f32_16x16x32_bf16 v[10:13], v[162:165], v[226:229], v[10:13]
	s_setprio 0
	s_setprio 1
	v_mfma_f32_16x16x32_bf16 v[54:57], v[166:169], v[184:187], v[54:57]
	v_mfma_f32_16x16x32_bf16 v[50:53], v[174:177], v[184:187], v[50:53]
	v_mfma_f32_16x16x32_bf16 v[38:41], v[166:169], v[196:199], v[38:41]
	v_mfma_f32_16x16x32_bf16 v[34:37], v[174:177], v[196:199], v[34:37]
	v_mfma_f32_16x16x32_bf16 v[22:25], v[166:169], v[214:217], v[22:25]
	v_mfma_f32_16x16x32_bf16 v[18:21], v[174:177], v[214:217], v[18:21]
	v_mfma_f32_16x16x32_bf16 v[6:9], v[166:169], v[222:225], v[6:9]
	v_mfma_f32_16x16x32_bf16 v[2:5], v[174:177], v[222:225], v[2:5]
	v_mfma_f32_16x16x32_bf16 v[54:57], v[170:173], v[188:191], v[54:57]
	v_mfma_f32_16x16x32_bf16 v[50:53], v[178:181], v[188:191], v[50:53]
	v_mfma_f32_16x16x32_bf16 v[38:41], v[170:173], v[210:213], v[38:41]
	v_mfma_f32_16x16x32_bf16 v[34:37], v[178:181], v[210:213], v[34:37]
	v_mfma_f32_16x16x32_bf16 v[22:25], v[170:173], v[218:221], v[22:25]
	v_mfma_f32_16x16x32_bf16 v[18:21], v[178:181], v[218:221], v[18:21]
	v_mfma_f32_16x16x32_bf16 v[6:9], v[170:173], v[226:229], v[6:9]
	v_mfma_f32_16x16x32_bf16 v[2:5], v[178:181], v[226:229], v[2:5]
	s_setprio 0
	s_barrier
	s_add_i32 s28, 0, 0x18000
	v_add_u32_e32 v157, s28, v153
	s_add_i32 s43, 0, 0x1c000
	ds_read_b128 v[130:133], v157
	ds_read_b128 v[148:151], v157 offset:1024
	ds_read_b128 v[158:161], v157 offset:2048
	ds_read_b128 v[162:165], v157 offset:3072
	v_add_u32_e32 v157, s43, v153
	ds_read_b128 v[166:169], v157
	ds_read_b128 v[170:173], v157 offset:1024
	ds_read_b128 v[174:177], v157 offset:2048
	ds_read_b128 v[178:181], v157 offset:3072
	s_add_u32 s52, s52, 0x40000
	s_addc_u32 s53, s53, 0
	s_mov_b32 m0, s59
	v_lshl_add_u64 v[234:235], s[52:53], 0, v[138:139]
	ds_read_b128 v[184:187], v156 offset:32768
	ds_read_b128 v[188:191], v156 offset:33792
	ds_read_b128 v[196:199], v156 offset:34816
	ds_read_b128 v[210:213], v156 offset:35840
	ds_read_b128 v[214:217], v156 offset:36864
	ds_read_b128 v[218:221], v156 offset:37888
	ds_read_b128 v[222:225], v156 offset:38912
	ds_read_b128 v[226:229], v156 offset:39936
	global_load_lds_dwordx4 v[234:235], off
	v_lshl_add_u64 v[234:235], s[52:53], 0, v[136:137]
	s_mov_b32 m0, s60
	s_nop 0
	global_load_lds_dwordx4 v[234:235], off
	s_waitcnt vmcnt(8)
	s_waitcnt lgkmcnt(0)
	s_barrier
	s_setprio 1
	s_waitcnt lgkmcnt(0)
	v_mfma_f32_16x16x32_bf16 v[126:129], v[130:133], v[184:187], v[126:129]
	v_mfma_f32_16x16x32_bf16 v[122:125], v[158:161], v[184:187], v[122:125]
	v_mfma_f32_16x16x32_bf16 v[110:113], v[130:133], v[196:199], v[110:113]
	v_mfma_f32_16x16x32_bf16 v[106:109], v[158:161], v[196:199], v[106:109]
	v_mfma_f32_16x16x32_bf16 v[94:97], v[130:133], v[214:217], v[94:97]
	v_mfma_f32_16x16x32_bf16 v[90:93], v[158:161], v[214:217], v[90:93]
	v_mfma_f32_16x16x32_bf16 v[78:81], v[130:133], v[222:225], v[78:81]
	v_mfma_f32_16x16x32_bf16 v[74:77], v[158:161], v[222:225], v[74:77]
	v_mfma_f32_16x16x32_bf16 v[126:129], v[148:151], v[188:191], v[126:129]
	v_mfma_f32_16x16x32_bf16 v[122:125], v[162:165], v[188:191], v[122:125]
	v_mfma_f32_16x16x32_bf16 v[110:113], v[148:151], v[210:213], v[110:113]
	v_mfma_f32_16x16x32_bf16 v[106:109], v[162:165], v[210:213], v[106:109]
	v_mfma_f32_16x16x32_bf16 v[94:97], v[148:151], v[218:221], v[94:97]
	v_mfma_f32_16x16x32_bf16 v[90:93], v[162:165], v[218:221], v[90:93]
	v_mfma_f32_16x16x32_bf16 v[78:81], v[148:151], v[226:229], v[78:81]
	v_mfma_f32_16x16x32_bf16 v[74:77], v[162:165], v[226:229], v[74:77]
	s_setprio 0
	s_setprio 1
	v_mfma_f32_16x16x32_bf16 v[118:121], v[166:169], v[184:187], v[118:121]
	v_mfma_f32_16x16x32_bf16 v[114:117], v[174:177], v[184:187], v[114:117]
	v_mfma_f32_16x16x32_bf16 v[102:105], v[166:169], v[196:199], v[102:105]
	v_mfma_f32_16x16x32_bf16 v[98:101], v[174:177], v[196:199], v[98:101]
	v_mfma_f32_16x16x32_bf16 v[86:89], v[166:169], v[214:217], v[86:89]
	v_mfma_f32_16x16x32_bf16 v[82:85], v[174:177], v[214:217], v[82:85]
	v_mfma_f32_16x16x32_bf16 v[70:73], v[166:169], v[222:225], v[70:73]
	v_mfma_f32_16x16x32_bf16 v[66:69], v[174:177], v[222:225], v[66:69]
	v_mfma_f32_16x16x32_bf16 v[118:121], v[170:173], v[188:191], v[118:121]
	v_mfma_f32_16x16x32_bf16 v[114:117], v[178:181], v[188:191], v[114:117]
	v_mfma_f32_16x16x32_bf16 v[102:105], v[170:173], v[210:213], v[102:105]
	v_mfma_f32_16x16x32_bf16 v[98:101], v[178:181], v[210:213], v[98:101]
	v_mfma_f32_16x16x32_bf16 v[86:89], v[170:173], v[218:221], v[86:89]
	v_mfma_f32_16x16x32_bf16 v[82:85], v[178:181], v[218:221], v[82:85]
	v_mfma_f32_16x16x32_bf16 v[70:73], v[170:173], v[226:229], v[70:73]
	v_mfma_f32_16x16x32_bf16 v[66:69], v[178:181], v[226:229], v[66:69]
	s_setprio 0
	s_barrier
	s_add_i32 s28, s28, s17
	v_lshl_add_u64 v[192:193], v[192:193], 0, s[22:23]
	s_mov_b32 m0, s28
	ds_read_b128 v[184:187], v156 offset:49152
	ds_read_b128 v[188:191], v156 offset:50176
	ds_read_b128 v[196:199], v156 offset:51200
	ds_read_b128 v[210:213], v156 offset:52224
	ds_read_b128 v[214:217], v156 offset:53248
	ds_read_b128 v[218:221], v156 offset:54272
	ds_read_b128 v[222:225], v156 offset:55296
	ds_read_b128 v[226:229], v156 offset:56320
	global_load_lds_dwordx4 v[192:193], off
	s_add_i32 m0, s28, 0x2000
	s_add_u32 s36, s36, 0x40080
	v_lshl_add_u64 v[192:193], v[202:203], 0, s[22:23]
	s_addc_u32 s37, s37, 0
	s_add_i32 s28, s43, s17
	global_load_lds_dwordx4 v[192:193], off
	v_lshl_add_u64 v[192:193], s[36:37], 0, v[0:1]
	s_mov_b32 m0, s28
	s_nop 0
	global_load_lds_dwordx4 v[192:193], off
	v_lshl_add_u64 v[192:193], s[36:37], 0, v[134:135]
	s_add_i32 m0, s28, 0x2000
	s_nop 0
	global_load_lds_dwordx4 v[192:193], off
	v_lshl_add_u64 v[192:193], v[230:231], 0, s[22:23]
	s_mov_b32 m0, s62
	s_nop 0
	global_load_lds_dwordx4 v[192:193], off
	v_lshl_add_u64 v[192:193], v[232:233], 0, s[22:23]
	s_mov_b32 m0, s63
	s_nop 0
	global_load_lds_dwordx4 v[192:193], off
	s_waitcnt vmcnt(8)
	s_waitcnt lgkmcnt(0)
	s_barrier
	s_setprio 1
	s_waitcnt lgkmcnt(0)
	v_mfma_f32_16x16x32_bf16 v[62:65], v[130:133], v[184:187], v[62:65]
	v_mfma_f32_16x16x32_bf16 v[58:61], v[158:161], v[184:187], v[58:61]
	v_mfma_f32_16x16x32_bf16 v[46:49], v[130:133], v[196:199], v[46:49]
	v_mfma_f32_16x16x32_bf16 v[42:45], v[158:161], v[196:199], v[42:45]
	v_mfma_f32_16x16x32_bf16 v[30:33], v[130:133], v[214:217], v[30:33]
	v_mfma_f32_16x16x32_bf16 v[26:29], v[158:161], v[214:217], v[26:29]
	v_mfma_f32_16x16x32_bf16 v[14:17], v[130:133], v[222:225], v[14:17]
	v_mfma_f32_16x16x32_bf16 v[10:13], v[158:161], v[222:225], v[10:13]
	v_mfma_f32_16x16x32_bf16 v[62:65], v[148:151], v[188:191], v[62:65]
	v_mfma_f32_16x16x32_bf16 v[58:61], v[162:165], v[188:191], v[58:61]
	v_mfma_f32_16x16x32_bf16 v[46:49], v[148:151], v[210:213], v[46:49]
	v_mfma_f32_16x16x32_bf16 v[42:45], v[162:165], v[210:213], v[42:45]
	v_mfma_f32_16x16x32_bf16 v[30:33], v[148:151], v[218:221], v[30:33]
	v_mfma_f32_16x16x32_bf16 v[26:29], v[162:165], v[218:221], v[26:29]
	v_mfma_f32_16x16x32_bf16 v[14:17], v[148:151], v[226:229], v[14:17]
	v_mfma_f32_16x16x32_bf16 v[10:13], v[162:165], v[226:229], v[10:13]
	s_setprio 0
	s_setprio 1
	v_mfma_f32_16x16x32_bf16 v[54:57], v[166:169], v[184:187], v[54:57]
	v_mfma_f32_16x16x32_bf16 v[50:53], v[174:177], v[184:187], v[50:53]
	v_mfma_f32_16x16x32_bf16 v[38:41], v[166:169], v[196:199], v[38:41]
	v_mfma_f32_16x16x32_bf16 v[34:37], v[174:177], v[196:199], v[34:37]
	v_mfma_f32_16x16x32_bf16 v[22:25], v[166:169], v[214:217], v[22:25]
	v_mfma_f32_16x16x32_bf16 v[18:21], v[174:177], v[214:217], v[18:21]
	v_mfma_f32_16x16x32_bf16 v[6:9], v[166:169], v[222:225], v[6:9]
	v_mfma_f32_16x16x32_bf16 v[2:5], v[174:177], v[222:225], v[2:5]
	v_mfma_f32_16x16x32_bf16 v[54:57], v[170:173], v[188:191], v[54:57]
	v_mfma_f32_16x16x32_bf16 v[50:53], v[178:181], v[188:191], v[50:53]
	v_mfma_f32_16x16x32_bf16 v[38:41], v[170:173], v[210:213], v[38:41]
	v_mfma_f32_16x16x32_bf16 v[34:37], v[178:181], v[210:213], v[34:37]
	v_mfma_f32_16x16x32_bf16 v[22:25], v[170:173], v[218:221], v[22:25]
	v_mfma_f32_16x16x32_bf16 v[18:21], v[178:181], v[218:221], v[18:21]
	v_mfma_f32_16x16x32_bf16 v[6:9], v[170:173], v[226:229], v[6:9]
	v_mfma_f32_16x16x32_bf16 v[2:5], v[178:181], v[226:229], v[2:5]
	s_setprio 0
	s_add_i32 s26, s26, 2
	s_add_u32 s30, s30, 0x100
	s_addc_u32 s31, s31, 0
	s_add_u32 s24, s24, 0x100
	s_addc_u32 s25, s25, 0
	s_cmp_gt_u32 s26, 13
	s_cbranch_scc1 .Lrot_exit_0
	s_add_u32 s28, s30, 0xfffc0080
	s_addc_u32 s36, s31, -1
	s_add_i32 s43, 0, 0x10000
	s_cmp_eq_u32 s26, 12
	s_cselect_b32 s53, s2, s36
	s_cselect_b32 s52, s3, s28
	v_add_u32_e32 v157, s43, v153
	s_cselect_b32 s37, s13, s25
	s_cselect_b32 s36, s16, s24
	s_add_i32 s28, 0, 0x14000
	s_barrier
	s_branch .Lrot_body_0
.Lrot_exit_0:
	s_barrier
	s_and_b64 vcc, exec, s[34:35]
	s_cbranch_vccz .LBB0_227
	s_barrier
	v_lshl_add_u32 v148, s12, 8, v152
	s_cmp_lt_i32 s74, s64
	s_mov_b64 s[12:13], -1
	s_cbranch_scc0 .LBB0_228

.Lrot_body_1:
	ds_read_b128 v[140:143], v156
	ds_read_b128 v[148:151], v156 offset:1024
	ds_read_b128 v[152:155], v156 offset:2048
	ds_read_b128 v[156:159], v156 offset:3072
	ds_read_b128 v[160:163], v172
	ds_read_b128 v[164:167], v172 offset:1024
	ds_read_b128 v[168:171], v172 offset:2048
	ds_read_b128 v[172:175], v172 offset:3072
	v_lshl_add_u64 v[180:181], s[12:13], 0, v[136:137]
	s_add_i32 m0, s51, 0xc000
	ds_read_b128 v[176:179], v147
	ds_read_b128 v[184:187], v147 offset:1024
	ds_read_b128 v[188:191], v147 offset:2048
	ds_read_b128 v[196:199], v147 offset:3072
	ds_read_b128 v[210:213], v147 offset:4096
	ds_read_b128 v[214:217], v147 offset:5120
	ds_read_b128 v[218:221], v147 offset:6144
	ds_read_b128 v[222:225], v147 offset:7168
	global_load_lds_dwordx4 v[180:181], off
	v_lshl_add_u64 v[180:181], s[12:13], 0, v[138:139]
	s_add_i32 m0, s51, 0xe000
	s_nop 0
	global_load_lds_dwordx4 v[180:181], off
	s_waitcnt vmcnt(8)
	s_waitcnt lgkmcnt(0)
	s_barrier
	s_setprio 1
	s_waitcnt lgkmcnt(0)
	v_mfma_f32_16x16x32_bf16 v[126:129], v[140:143], v[176:179], v[126:129]
	v_mfma_f32_16x16x32_bf16 v[122:125], v[152:155], v[176:179], v[122:125]
	v_mfma_f32_16x16x32_bf16 v[110:113], v[140:143], v[188:191], v[110:113]
	v_mfma_f32_16x16x32_bf16 v[106:109], v[152:155], v[188:191], v[106:109]
	v_mfma_f32_16x16x32_bf16 v[94:97], v[140:143], v[210:213], v[94:97]
	v_mfma_f32_16x16x32_bf16 v[90:93], v[152:155], v[210:213], v[90:93]
	v_mfma_f32_16x16x32_bf16 v[78:81], v[140:143], v[218:221], v[78:81]
	v_mfma_f32_16x16x32_bf16 v[74:77], v[152:155], v[218:221], v[74:77]
	v_mfma_f32_16x16x32_bf16 v[126:129], v[148:151], v[184:187], v[126:129]
	v_mfma_f32_16x16x32_bf16 v[122:125], v[156:159], v[184:187], v[122:125]
	v_mfma_f32_16x16x32_bf16 v[110:113], v[148:151], v[196:199], v[110:113]
	v_mfma_f32_16x16x32_bf16 v[106:109], v[156:159], v[196:199], v[106:109]
	v_mfma_f32_16x16x32_bf16 v[94:97], v[148:151], v[214:217], v[94:97]
	v_mfma_f32_16x16x32_bf16 v[90:93], v[156:159], v[214:217], v[90:93]
	v_mfma_f32_16x16x32_bf16 v[78:81], v[148:151], v[222:225], v[78:81]
	v_mfma_f32_16x16x32_bf16 v[74:77], v[156:159], v[222:225], v[74:77]
	s_setprio 0
	s_setprio 1
	v_mfma_f32_16x16x32_bf16 v[118:121], v[160:163], v[176:179], v[118:121]
	v_mfma_f32_16x16x32_bf16 v[114:117], v[168:171], v[176:179], v[114:117]
	v_mfma_f32_16x16x32_bf16 v[102:105], v[160:163], v[188:191], v[102:105]
	v_mfma_f32_16x16x32_bf16 v[98:101], v[168:171], v[188:191], v[98:101]
	v_mfma_f32_16x16x32_bf16 v[86:89], v[160:163], v[210:213], v[86:89]
	v_mfma_f32_16x16x32_bf16 v[82:85], v[168:171], v[210:213], v[82:85]
	v_mfma_f32_16x16x32_bf16 v[70:73], v[160:163], v[218:221], v[70:73]
	v_mfma_f32_16x16x32_bf16 v[66:69], v[168:171], v[218:221], v[66:69]
	v_mfma_f32_16x16x32_bf16 v[118:121], v[164:167], v[184:187], v[118:121]
	v_mfma_f32_16x16x32_bf16 v[114:117], v[172:175], v[184:187], v[114:117]
	v_mfma_f32_16x16x32_bf16 v[102:105], v[164:167], v[196:199], v[102:105]
	v_mfma_f32_16x16x32_bf16 v[98:101], v[172:175], v[196:199], v[98:101]
	v_mfma_f32_16x16x32_bf16 v[86:89], v[164:167], v[214:217], v[86:89]
	v_mfma_f32_16x16x32_bf16 v[82:85], v[172:175], v[214:217], v[82:85]
	v_mfma_f32_16x16x32_bf16 v[70:73], v[164:167], v[222:225], v[70:73]
	v_mfma_f32_16x16x32_bf16 v[66:69], v[172:175], v[222:225], v[66:69]
	s_setprio 0
	s_barrier
	s_add_i32 s45, s45, s50
	v_lshl_add_u64 v[180:181], s[30:31], 0, v[0:1]
	s_mov_b32 m0, s45
	ds_read_b128 v[176:179], v147 offset:16384
	ds_read_b128 v[184:187], v147 offset:17408
	ds_read_b128 v[188:191], v147 offset:18432
	ds_read_b128 v[196:199], v147 offset:19456
	ds_read_b128 v[210:213], v147 offset:20480
	ds_read_b128 v[214:217], v147 offset:21504
	ds_read_b128 v[218:221], v147 offset:22528
	ds_read_b128 v[222:225], v147 offset:23552
	global_load_lds_dwordx4 v[180:181], off
	s_add_i32 m0, s45, 0x2000
	s_add_u32 s60, s30, 0x40000
	v_lshl_add_u64 v[192:193], s[30:31], 0, v[130:131]
	s_addc_u32 s61, s31, 0
	s_add_i32 s45, s59, s50
	global_load_lds_dwordx4 v[192:193], off
	v_lshl_add_u64 v[202:203], s[60:61], 0, v[0:1]
	s_mov_b32 m0, s45
	v_lshl_add_u64 v[226:227], s[36:37], 0, v[132:133]
	global_load_lds_dwordx4 v[202:203], off
	v_lshl_add_u64 v[202:203], s[60:61], 0, v[130:131]
	s_add_i32 m0, s45, 0x2000
	s_nop 0
	global_load_lds_dwordx4 v[202:203], off
	v_lshl_add_u64 v[202:203], s[36:37], 0, v[134:135]
	s_mov_b32 m0, s51
	s_nop 0
	global_load_lds_dwordx4 v[202:203], off
	s_mov_b32 m0, s52
	s_nop 0
	global_load_lds_dwordx4 v[226:227], off
	s_waitcnt vmcnt(8)
	s_waitcnt lgkmcnt(0)
	s_barrier
	s_setprio 1
	s_waitcnt lgkmcnt(0)
	v_mfma_f32_16x16x32_bf16 v[62:65], v[140:143], v[176:179], v[62:65]
	v_mfma_f32_16x16x32_bf16 v[58:61], v[152:155], v[176:179], v[58:61]
	v_mfma_f32_16x16x32_bf16 v[46:49], v[140:143], v[188:191], v[46:49]
	v_mfma_f32_16x16x32_bf16 v[42:45], v[152:155], v[188:191], v[42:45]
	v_mfma_f32_16x16x32_bf16 v[30:33], v[140:143], v[210:213], v[30:33]
	v_mfma_f32_16x16x32_bf16 v[26:29], v[152:155], v[210:213], v[26:29]
	v_mfma_f32_16x16x32_bf16 v[14:17], v[140:143], v[218:221], v[14:17]
	v_mfma_f32_16x16x32_bf16 v[10:13], v[152:155], v[218:221], v[10:13]
	v_mfma_f32_16x16x32_bf16 v[62:65], v[148:151], v[184:187], v[62:65]
	v_mfma_f32_16x16x32_bf16 v[58:61], v[156:159], v[184:187], v[58:61]
	v_mfma_f32_16x16x32_bf16 v[46:49], v[148:151], v[196:199], v[46:49]
	v_mfma_f32_16x16x32_bf16 v[42:45], v[156:159], v[196:199], v[42:45]
	v_mfma_f32_16x16x32_bf16 v[30:33], v[148:151], v[214:217], v[30:33]
	v_mfma_f32_16x16x32_bf16 v[26:29], v[156:159], v[214:217], v[26:29]
	v_mfma_f32_16x16x32_bf16 v[14:17], v[148:151], v[222:225], v[14:17]
	v_mfma_f32_16x16x32_bf16 v[10:13], v[156:159], v[222:225], v[10:13]
	s_setprio 0
	s_setprio 1
	v_mfma_f32_16x16x32_bf16 v[54:57], v[160:163], v[176:179], v[54:57]
	v_mfma_f32_16x16x32_bf16 v[50:53], v[168:171], v[176:179], v[50:53]
	v_mfma_f32_16x16x32_bf16 v[38:41], v[160:163], v[188:191], v[38:41]
	v_mfma_f32_16x16x32_bf16 v[34:37], v[168:171], v[188:191], v[34:37]
	v_mfma_f32_16x16x32_bf16 v[22:25], v[160:163], v[210:213], v[22:25]
	v_mfma_f32_16x16x32_bf16 v[18:21], v[168:171], v[210:213], v[18:21]
	v_mfma_f32_16x16x32_bf16 v[6:9], v[160:163], v[218:221], v[6:9]
	v_mfma_f32_16x16x32_bf16 v[2:5], v[168:171], v[218:221], v[2:5]
	v_mfma_f32_16x16x32_bf16 v[54:57], v[164:167], v[184:187], v[54:57]
	v_mfma_f32_16x16x32_bf16 v[50:53], v[172:175], v[184:187], v[50:53]
	v_mfma_f32_16x16x32_bf16 v[38:41], v[164:167], v[196:199], v[38:41]
	v_mfma_f32_16x16x32_bf16 v[34:37], v[172:175], v[196:199], v[34:37]
	v_mfma_f32_16x16x32_bf16 v[22:25], v[164:167], v[214:217], v[22:25]
	v_mfma_f32_16x16x32_bf16 v[18:21], v[172:175], v[214:217], v[18:21]
	v_mfma_f32_16x16x32_bf16 v[6:9], v[164:167], v[222:225], v[6:9]
	v_mfma_f32_16x16x32_bf16 v[2:5], v[172:175], v[222:225], v[2:5]
	s_setprio 0
	s_barrier
	s_add_i32 s45, 0, 0x18000
	s_add_i32 s59, 0, 0x1c000
	v_add_u32_e32 v156, s45, v145
	v_add_u32_e32 v172, s59, v145
	ds_read_b128 v[140:143], v156
	ds_read_b128 v[148:151], v156 offset:1024
	ds_read_b128 v[152:155], v156 offset:2048
	ds_read_b128 v[156:159], v156 offset:3072
	ds_read_b128 v[160:163], v172
	ds_read_b128 v[164:167], v172 offset:1024
	ds_read_b128 v[168:171], v172 offset:2048
	ds_read_b128 v[172:175], v172 offset:3072
	s_add_u32 s36, s36, 0x40000
	s_addc_u32 s37, s37, 0
	s_mov_b32 m0, s53
	v_lshl_add_u64 v[228:229], s[36:37], 0, v[134:135]
	ds_read_b128 v[176:179], v147 offset:32768
	ds_read_b128 v[184:187], v147 offset:33792
	ds_read_b128 v[188:191], v147 offset:34816
	ds_read_b128 v[196:199], v147 offset:35840
	ds_read_b128 v[210:213], v147 offset:36864
	ds_read_b128 v[214:217], v147 offset:37888
	ds_read_b128 v[218:221], v147 offset:38912
	ds_read_b128 v[222:225], v147 offset:39936
	global_load_lds_dwordx4 v[228:229], off
	v_lshl_add_u64 v[228:229], s[36:37], 0, v[132:133]
	s_mov_b32 m0, s54
	s_nop 0
	global_load_lds_dwordx4 v[228:229], off
	s_waitcnt vmcnt(8)
	s_waitcnt lgkmcnt(0)
	s_barrier
	s_setprio 1
	s_waitcnt lgkmcnt(0)
	v_mfma_f32_16x16x32_bf16 v[126:129], v[140:143], v[176:179], v[126:129]
	v_mfma_f32_16x16x32_bf16 v[122:125], v[152:155], v[176:179], v[122:125]
	v_mfma_f32_16x16x32_bf16 v[110:113], v[140:143], v[188:191], v[110:113]
	v_mfma_f32_16x16x32_bf16 v[106:109], v[152:155], v[188:191], v[106:109]
	v_mfma_f32_16x16x32_bf16 v[94:97], v[140:143], v[210:213], v[94:97]
	v_mfma_f32_16x16x32_bf16 v[90:93], v[152:155], v[210:213], v[90:93]
	v_mfma_f32_16x16x32_bf16 v[78:81], v[140:143], v[218:221], v[78:81]
	v_mfma_f32_16x16x32_bf16 v[74:77], v[152:155], v[218:221], v[74:77]
	v_mfma_f32_16x16x32_bf16 v[126:129], v[148:151], v[184:187], v[126:129]
	v_mfma_f32_16x16x32_bf16 v[122:125], v[156:159], v[184:187], v[122:125]
	v_mfma_f32_16x16x32_bf16 v[110:113], v[148:151], v[196:199], v[110:113]
	v_mfma_f32_16x16x32_bf16 v[106:109], v[156:159], v[196:199], v[106:109]
	v_mfma_f32_16x16x32_bf16 v[94:97], v[148:151], v[214:217], v[94:97]
	v_mfma_f32_16x16x32_bf16 v[90:93], v[156:159], v[214:217], v[90:93]
	v_mfma_f32_16x16x32_bf16 v[78:81], v[148:151], v[222:225], v[78:81]
	v_mfma_f32_16x16x32_bf16 v[74:77], v[156:159], v[222:225], v[74:77]
	s_setprio 0
	s_setprio 1
	v_mfma_f32_16x16x32_bf16 v[118:121], v[160:163], v[176:179], v[118:121]
	v_mfma_f32_16x16x32_bf16 v[114:117], v[168:171], v[176:179], v[114:117]
	v_mfma_f32_16x16x32_bf16 v[102:105], v[160:163], v[188:191], v[102:105]
	v_mfma_f32_16x16x32_bf16 v[98:101], v[168:171], v[188:191], v[98:101]
	v_mfma_f32_16x16x32_bf16 v[86:89], v[160:163], v[210:213], v[86:89]
	v_mfma_f32_16x16x32_bf16 v[82:85], v[168:171], v[210:213], v[82:85]
	v_mfma_f32_16x16x32_bf16 v[70:73], v[160:163], v[218:221], v[70:73]
	v_mfma_f32_16x16x32_bf16 v[66:69], v[168:171], v[218:221], v[66:69]
	v_mfma_f32_16x16x32_bf16 v[118:121], v[164:167], v[184:187], v[118:121]
	v_mfma_f32_16x16x32_bf16 v[114:117], v[172:175], v[184:187], v[114:117]
	v_mfma_f32_16x16x32_bf16 v[102:105], v[164:167], v[196:199], v[102:105]
	v_mfma_f32_16x16x32_bf16 v[98:101], v[172:175], v[196:199], v[98:101]
	v_mfma_f32_16x16x32_bf16 v[86:89], v[164:167], v[214:217], v[86:89]
	v_mfma_f32_16x16x32_bf16 v[82:85], v[172:175], v[214:217], v[82:85]
	v_mfma_f32_16x16x32_bf16 v[70:73], v[164:167], v[222:225], v[70:73]
	v_mfma_f32_16x16x32_bf16 v[66:69], v[172:175], v[222:225], v[66:69]
	s_setprio 0
	s_barrier
	s_add_i32 s36, s45, s50
	v_lshl_add_u64 v[180:181], v[180:181], 0, s[22:23]
	s_mov_b32 m0, s36
	ds_read_b128 v[176:179], v147 offset:49152
	ds_read_b128 v[184:187], v147 offset:50176
	ds_read_b128 v[188:191], v147 offset:51200
	ds_read_b128 v[196:199], v147 offset:52224
	ds_read_b128 v[210:213], v147 offset:53248
	ds_read_b128 v[214:217], v147 offset:54272
	ds_read_b128 v[218:221], v147 offset:55296
	ds_read_b128 v[222:225], v147 offset:56320
	global_load_lds_dwordx4 v[180:181], off
	s_add_i32 m0, s36, 0x2000
	s_add_u32 s30, s30, 0x40080
	v_lshl_add_u64 v[180:181], v[192:193], 0, s[22:23]
	s_addc_u32 s31, s31, 0
	s_add_i32 s36, s59, s50
	global_load_lds_dwordx4 v[180:181], off
	v_lshl_add_u64 v[180:181], s[30:31], 0, v[0:1]
	s_mov_b32 m0, s36
	s_nop 0
	global_load_lds_dwordx4 v[180:181], off
	v_lshl_add_u64 v[180:181], s[30:31], 0, v[130:131]
	s_add_i32 m0, s36, 0x2000
	s_nop 0
	global_load_lds_dwordx4 v[180:181], off
	v_lshl_add_u64 v[180:181], v[202:203], 0, s[22:23]
	s_mov_b32 m0, s56
	s_nop 0
	global_load_lds_dwordx4 v[180:181], off
	v_lshl_add_u64 v[180:181], v[226:227], 0, s[22:23]
	s_mov_b32 m0, s57
	s_nop 0
	global_load_lds_dwordx4 v[180:181], off
	s_waitcnt vmcnt(8)
	s_waitcnt lgkmcnt(0)
	s_barrier
	s_setprio 1
	s_waitcnt lgkmcnt(0)
	v_mfma_f32_16x16x32_bf16 v[62:65], v[140:143], v[176:179], v[62:65]
	v_mfma_f32_16x16x32_bf16 v[58:61], v[152:155], v[176:179], v[58:61]
	v_mfma_f32_16x16x32_bf16 v[46:49], v[140:143], v[188:191], v[46:49]
	v_mfma_f32_16x16x32_bf16 v[42:45], v[152:155], v[188:191], v[42:45]
	v_mfma_f32_16x16x32_bf16 v[30:33], v[140:143], v[210:213], v[30:33]
	v_mfma_f32_16x16x32_bf16 v[26:29], v[152:155], v[210:213], v[26:29]
	v_mfma_f32_16x16x32_bf16 v[14:17], v[140:143], v[218:221], v[14:17]
	v_mfma_f32_16x16x32_bf16 v[10:13], v[152:155], v[218:221], v[10:13]
	v_mfma_f32_16x16x32_bf16 v[62:65], v[148:151], v[184:187], v[62:65]
	v_mfma_f32_16x16x32_bf16 v[58:61], v[156:159], v[184:187], v[58:61]
	v_mfma_f32_16x16x32_bf16 v[46:49], v[148:151], v[196:199], v[46:49]
	v_mfma_f32_16x16x32_bf16 v[42:45], v[156:159], v[196:199], v[42:45]
	v_mfma_f32_16x16x32_bf16 v[30:33], v[148:151], v[214:217], v[30:33]
	v_mfma_f32_16x16x32_bf16 v[26:29], v[156:159], v[214:217], v[26:29]
	v_mfma_f32_16x16x32_bf16 v[14:17], v[148:151], v[222:225], v[14:17]
	v_mfma_f32_16x16x32_bf16 v[10:13], v[156:159], v[222:225], v[10:13]
	s_setprio 0
	s_setprio 1
	v_mfma_f32_16x16x32_bf16 v[54:57], v[160:163], v[176:179], v[54:57]
	v_mfma_f32_16x16x32_bf16 v[50:53], v[168:171], v[176:179], v[50:53]
	v_mfma_f32_16x16x32_bf16 v[38:41], v[160:163], v[188:191], v[38:41]
	v_mfma_f32_16x16x32_bf16 v[34:37], v[168:171], v[188:191], v[34:37]
	v_mfma_f32_16x16x32_bf16 v[22:25], v[160:163], v[210:213], v[22:25]
	v_mfma_f32_16x16x32_bf16 v[18:21], v[168:171], v[210:213], v[18:21]
	v_mfma_f32_16x16x32_bf16 v[6:9], v[160:163], v[218:221], v[6:9]
	v_mfma_f32_16x16x32_bf16 v[2:5], v[168:171], v[218:221], v[2:5]
	v_mfma_f32_16x16x32_bf16 v[54:57], v[164:167], v[184:187], v[54:57]
	v_mfma_f32_16x16x32_bf16 v[50:53], v[172:175], v[184:187], v[50:53]
	v_mfma_f32_16x16x32_bf16 v[38:41], v[164:167], v[196:199], v[38:41]
	v_mfma_f32_16x16x32_bf16 v[34:37], v[172:175], v[196:199], v[34:37]
	v_mfma_f32_16x16x32_bf16 v[22:25], v[164:167], v[214:217], v[22:25]
	v_mfma_f32_16x16x32_bf16 v[18:21], v[172:175], v[214:217], v[18:21]
	v_mfma_f32_16x16x32_bf16 v[6:9], v[164:167], v[222:225], v[6:9]
	v_mfma_f32_16x16x32_bf16 v[2:5], v[172:175], v[222:225], v[2:5]
	s_setprio 0
	s_add_i32 s35, s35, 2
	s_add_u32 s12, s12, 0x100
	s_addc_u32 s13, s13, 0
	s_add_u32 s26, s26, 0x100
	s_addc_u32 s28, s28, 0
	s_cmp_gt_u32 s35, 13
	s_cbranch_scc1 .Lrot_exit_1
	s_add_u32 s30, s12, 0xfffc0080
	s_addc_u32 s31, s13, -1
	s_add_i32 s45, 0, 0x10000
	s_cmp_eq_u32 s35, 12
	s_cselect_b32 s37, s3, s31
	s_cselect_b32 s36, s16, s30
	s_cselect_b32 s31, s24, s28
	s_cselect_b32 s30, s25, s26
	s_add_i32 s59, 0, 0x14000
	v_add_u32_e32 v156, s45, v145
	v_add_u32_e32 v172, s59, v145
	s_barrier
	s_branch .Lrot_body_1
.Lrot_exit_1:
	s_barrier
	s_and_b64 vcc, exec, s[20:21]
	s_cbranch_vccz .LBB0_698
	s_barrier

.Lrot_body_2:
	ds_read_b128 v[140:143], v149
	ds_read_b128 v[150:153], v149 offset:1024
	ds_read_b128 v[154:157], v149 offset:2048
	ds_read_b128 v[158:161], v149 offset:3072
	v_add_u32_e32 v149, s54, v145
	ds_read_b128 v[162:165], v149
	ds_read_b128 v[166:169], v149 offset:1024
	ds_read_b128 v[170:173], v149 offset:2048
	ds_read_b128 v[174:177], v149 offset:3072
	v_lshl_add_u64 v[192:193], s[34:35], 0, v[136:137]
	s_add_i32 m0, s18, 0xc000
	ds_read_b128 v[178:181], v148
	ds_read_b128 v[184:187], v148 offset:1024
	ds_read_b128 v[188:191], v148 offset:2048
	ds_read_b128 v[196:199], v148 offset:3072
	ds_read_b128 v[210:213], v148 offset:4096
	ds_read_b128 v[214:217], v148 offset:5120
	ds_read_b128 v[218:221], v148 offset:6144
	ds_read_b128 v[222:225], v148 offset:7168
	global_load_lds_dwordx4 v[192:193], off
	v_lshl_add_u64 v[192:193], s[34:35], 0, v[138:139]
	s_add_i32 m0, s18, 0xe000
	s_nop 0
	global_load_lds_dwordx4 v[192:193], off
	s_waitcnt vmcnt(8)
	s_waitcnt lgkmcnt(0)
	s_barrier
	s_setprio 1
	s_waitcnt lgkmcnt(0)
	v_mfma_f32_16x16x32_bf16 v[126:129], v[140:143], v[178:181], v[126:129]
	v_mfma_f32_16x16x32_bf16 v[122:125], v[154:157], v[178:181], v[122:125]
	v_mfma_f32_16x16x32_bf16 v[110:113], v[140:143], v[188:191], v[110:113]
	v_mfma_f32_16x16x32_bf16 v[106:109], v[154:157], v[188:191], v[106:109]
	v_mfma_f32_16x16x32_bf16 v[94:97], v[140:143], v[210:213], v[94:97]
	v_mfma_f32_16x16x32_bf16 v[90:93], v[154:157], v[210:213], v[90:93]
	v_mfma_f32_16x16x32_bf16 v[78:81], v[140:143], v[218:221], v[78:81]
	v_mfma_f32_16x16x32_bf16 v[74:77], v[154:157], v[218:221], v[74:77]
	v_mfma_f32_16x16x32_bf16 v[126:129], v[150:153], v[184:187], v[126:129]
	v_mfma_f32_16x16x32_bf16 v[122:125], v[158:161], v[184:187], v[122:125]
	v_mfma_f32_16x16x32_bf16 v[110:113], v[150:153], v[196:199], v[110:113]
	v_mfma_f32_16x16x32_bf16 v[106:109], v[158:161], v[196:199], v[106:109]
	v_mfma_f32_16x16x32_bf16 v[94:97], v[150:153], v[214:217], v[94:97]
	v_mfma_f32_16x16x32_bf16 v[90:93], v[158:161], v[214:217], v[90:93]
	v_mfma_f32_16x16x32_bf16 v[78:81], v[150:153], v[222:225], v[78:81]
	v_mfma_f32_16x16x32_bf16 v[74:77], v[158:161], v[222:225], v[74:77]
	s_setprio 0
	s_setprio 1
	v_mfma_f32_16x16x32_bf16 v[118:121], v[162:165], v[178:181], v[118:121]
	v_mfma_f32_16x16x32_bf16 v[114:117], v[170:173], v[178:181], v[114:117]
	v_mfma_f32_16x16x32_bf16 v[102:105], v[162:165], v[188:191], v[102:105]
	v_mfma_f32_16x16x32_bf16 v[98:101], v[170:173], v[188:191], v[98:101]
	v_mfma_f32_16x16x32_bf16 v[86:89], v[162:165], v[210:213], v[86:89]
	v_mfma_f32_16x16x32_bf16 v[82:85], v[170:173], v[210:213], v[82:85]
	v_mfma_f32_16x16x32_bf16 v[70:73], v[162:165], v[218:221], v[70:73]
	v_mfma_f32_16x16x32_bf16 v[66:69], v[170:173], v[218:221], v[66:69]
	v_mfma_f32_16x16x32_bf16 v[118:121], v[166:169], v[184:187], v[118:121]
	v_mfma_f32_16x16x32_bf16 v[114:117], v[174:177], v[184:187], v[114:117]
	v_mfma_f32_16x16x32_bf16 v[102:105], v[166:169], v[196:199], v[102:105]
	v_mfma_f32_16x16x32_bf16 v[98:101], v[174:177], v[196:199], v[98:101]
	v_mfma_f32_16x16x32_bf16 v[86:89], v[166:169], v[214:217], v[86:89]
	v_mfma_f32_16x16x32_bf16 v[82:85], v[174:177], v[214:217], v[82:85]
	v_mfma_f32_16x16x32_bf16 v[70:73], v[166:169], v[222:225], v[70:73]
	v_mfma_f32_16x16x32_bf16 v[66:69], v[174:177], v[222:225], v[66:69]
	s_setprio 0
	s_barrier
	s_add_i32 s51, s51, s0
	v_lshl_add_u64 v[192:193], s[36:37], 0, v[0:1]
	s_mov_b32 m0, s51
	ds_read_b128 v[178:181], v148 offset:16384
	ds_read_b128 v[184:187], v148 offset:17408
	ds_read_b128 v[188:191], v148 offset:18432
	ds_read_b128 v[196:199], v148 offset:19456
	ds_read_b128 v[210:213], v148 offset:20480
	ds_read_b128 v[214:217], v148 offset:21504
	ds_read_b128 v[218:221], v148 offset:22528
	ds_read_b128 v[222:225], v148 offset:23552
	global_load_lds_dwordx4 v[192:193], off
	s_add_i32 m0, s51, 0x2000
	s_add_u32 s52, s36, 0x40000
	v_lshl_add_u64 v[202:203], s[36:37], 0, v[130:131]
	s_addc_u32 s53, s37, 0
	s_add_i32 s51, s54, s0
	global_load_lds_dwordx4 v[202:203], off
	v_lshl_add_u64 v[226:227], s[52:53], 0, v[0:1]
	s_mov_b32 m0, s51
	v_lshl_add_u64 v[228:229], s[40:41], 0, v[132:133]
	global_load_lds_dwordx4 v[226:227], off
	v_lshl_add_u64 v[226:227], s[52:53], 0, v[130:131]
	s_add_i32 m0, s51, 0x2000
	s_nop 0
	global_load_lds_dwordx4 v[226:227], off
	v_lshl_add_u64 v[226:227], s[40:41], 0, v[134:135]
	s_mov_b32 m0, s18
	s_nop 0
	global_load_lds_dwordx4 v[226:227], off
	s_mov_b32 m0, s19
	s_nop 0
	global_load_lds_dwordx4 v[228:229], off
	s_waitcnt vmcnt(8)
	s_waitcnt lgkmcnt(0)
	s_barrier
	s_setprio 1
	s_waitcnt lgkmcnt(0)
	v_mfma_f32_16x16x32_bf16 v[62:65], v[140:143], v[178:181], v[62:65]
	v_mfma_f32_16x16x32_bf16 v[58:61], v[154:157], v[178:181], v[58:61]
	v_mfma_f32_16x16x32_bf16 v[46:49], v[140:143], v[188:191], v[46:49]
	v_mfma_f32_16x16x32_bf16 v[42:45], v[154:157], v[188:191], v[42:45]
	v_mfma_f32_16x16x32_bf16 v[30:33], v[140:143], v[210:213], v[30:33]
	v_mfma_f32_16x16x32_bf16 v[26:29], v[154:157], v[210:213], v[26:29]
	v_mfma_f32_16x16x32_bf16 v[14:17], v[140:143], v[218:221], v[14:17]
	v_mfma_f32_16x16x32_bf16 v[10:13], v[154:157], v[218:221], v[10:13]
	v_mfma_f32_16x16x32_bf16 v[62:65], v[150:153], v[184:187], v[62:65]
	v_mfma_f32_16x16x32_bf16 v[58:61], v[158:161], v[184:187], v[58:61]
	v_mfma_f32_16x16x32_bf16 v[46:49], v[150:153], v[196:199], v[46:49]
	v_mfma_f32_16x16x32_bf16 v[42:45], v[158:161], v[196:199], v[42:45]
	v_mfma_f32_16x16x32_bf16 v[30:33], v[150:153], v[214:217], v[30:33]
	v_mfma_f32_16x16x32_bf16 v[26:29], v[158:161], v[214:217], v[26:29]
	v_mfma_f32_16x16x32_bf16 v[14:17], v[150:153], v[222:225], v[14:17]
	v_mfma_f32_16x16x32_bf16 v[10:13], v[158:161], v[222:225], v[10:13]
	s_setprio 0
	s_setprio 1
	v_mfma_f32_16x16x32_bf16 v[54:57], v[162:165], v[178:181], v[54:57]
	v_mfma_f32_16x16x32_bf16 v[50:53], v[170:173], v[178:181], v[50:53]
	v_mfma_f32_16x16x32_bf16 v[38:41], v[162:165], v[188:191], v[38:41]
	v_mfma_f32_16x16x32_bf16 v[34:37], v[170:173], v[188:191], v[34:37]
	v_mfma_f32_16x16x32_bf16 v[22:25], v[162:165], v[210:213], v[22:25]
	v_mfma_f32_16x16x32_bf16 v[18:21], v[170:173], v[210:213], v[18:21]
	v_mfma_f32_16x16x32_bf16 v[6:9], v[162:165], v[218:221], v[6:9]
	v_mfma_f32_16x16x32_bf16 v[2:5], v[170:173], v[218:221], v[2:5]
	v_mfma_f32_16x16x32_bf16 v[54:57], v[166:169], v[184:187], v[54:57]
	v_mfma_f32_16x16x32_bf16 v[50:53], v[174:177], v[184:187], v[50:53]
	v_mfma_f32_16x16x32_bf16 v[38:41], v[166:169], v[196:199], v[38:41]
	v_mfma_f32_16x16x32_bf16 v[34:37], v[174:177], v[196:199], v[34:37]
	v_mfma_f32_16x16x32_bf16 v[22:25], v[166:169], v[214:217], v[22:25]
	v_mfma_f32_16x16x32_bf16 v[18:21], v[174:177], v[214:217], v[18:21]
	v_mfma_f32_16x16x32_bf16 v[6:9], v[166:169], v[222:225], v[6:9]
	v_mfma_f32_16x16x32_bf16 v[2:5], v[174:177], v[222:225], v[2:5]
	s_setprio 0
	s_barrier
	s_add_i32 s51, 0, 0x18000
	v_add_u32_e32 v149, s51, v145
	s_add_i32 s52, 0, 0x1c000
	ds_read_b128 v[140:143], v149
	ds_read_b128 v[150:153], v149 offset:1024
	ds_read_b128 v[154:157], v149 offset:2048
	ds_read_b128 v[158:161], v149 offset:3072
	v_add_u32_e32 v149, s52, v145
	ds_read_b128 v[162:165], v149
	ds_read_b128 v[166:169], v149 offset:1024
	ds_read_b128 v[170:173], v149 offset:2048
	ds_read_b128 v[174:177], v149 offset:3072
	s_add_u32 s40, s40, 0x40000
	s_addc_u32 s41, s41, 0
	s_mov_b32 m0, s24
	v_lshl_add_u64 v[230:231], s[40:41], 0, v[134:135]
	ds_read_b128 v[178:181], v148 offset:32768
	ds_read_b128 v[184:187], v148 offset:33792
	ds_read_b128 v[188:191], v148 offset:34816
	ds_read_b128 v[196:199], v148 offset:35840
	ds_read_b128 v[210:213], v148 offset:36864
	ds_read_b128 v[214:217], v148 offset:37888
	ds_read_b128 v[218:221], v148 offset:38912
	ds_read_b128 v[222:225], v148 offset:39936
	global_load_lds_dwordx4 v[230:231], off
	v_lshl_add_u64 v[230:231], s[40:41], 0, v[132:133]
	s_mov_b32 m0, s25
	s_nop 0
	global_load_lds_dwordx4 v[230:231], off
	s_waitcnt vmcnt(8)
	s_waitcnt lgkmcnt(0)
	s_barrier
	s_setprio 1
	s_waitcnt lgkmcnt(0)
	v_mfma_f32_16x16x32_bf16 v[126:129], v[140:143], v[178:181], v[126:129]
	v_mfma_f32_16x16x32_bf16 v[122:125], v[154:157], v[178:181], v[122:125]
	v_mfma_f32_16x16x32_bf16 v[110:113], v[140:143], v[188:191], v[110:113]
	v_mfma_f32_16x16x32_bf16 v[106:109], v[154:157], v[188:191], v[106:109]
	v_mfma_f32_16x16x32_bf16 v[94:97], v[140:143], v[210:213], v[94:97]
	v_mfma_f32_16x16x32_bf16 v[90:93], v[154:157], v[210:213], v[90:93]
	v_mfma_f32_16x16x32_bf16 v[78:81], v[140:143], v[218:221], v[78:81]
	v_mfma_f32_16x16x32_bf16 v[74:77], v[154:157], v[218:221], v[74:77]
	v_mfma_f32_16x16x32_bf16 v[126:129], v[150:153], v[184:187], v[126:129]
	v_mfma_f32_16x16x32_bf16 v[122:125], v[158:161], v[184:187], v[122:125]
	v_mfma_f32_16x16x32_bf16 v[110:113], v[150:153], v[196:199], v[110:113]
	v_mfma_f32_16x16x32_bf16 v[106:109], v[158:161], v[196:199], v[106:109]
	v_mfma_f32_16x16x32_bf16 v[94:97], v[150:153], v[214:217], v[94:97]
	v_mfma_f32_16x16x32_bf16 v[90:93], v[158:161], v[214:217], v[90:93]
	v_mfma_f32_16x16x32_bf16 v[78:81], v[150:153], v[222:225], v[78:81]
	v_mfma_f32_16x16x32_bf16 v[74:77], v[158:161], v[222:225], v[74:77]
	s_setprio 0
	s_setprio 1
	v_mfma_f32_16x16x32_bf16 v[118:121], v[162:165], v[178:181], v[118:121]
	v_mfma_f32_16x16x32_bf16 v[114:117], v[170:173], v[178:181], v[114:117]
	v_mfma_f32_16x16x32_bf16 v[102:105], v[162:165], v[188:191], v[102:105]
	v_mfma_f32_16x16x32_bf16 v[98:101], v[170:173], v[188:191], v[98:101]
	v_mfma_f32_16x16x32_bf16 v[86:89], v[162:165], v[210:213], v[86:89]
	v_mfma_f32_16x16x32_bf16 v[82:85], v[170:173], v[210:213], v[82:85]
	v_mfma_f32_16x16x32_bf16 v[70:73], v[162:165], v[218:221], v[70:73]
	v_mfma_f32_16x16x32_bf16 v[66:69], v[170:173], v[218:221], v[66:69]
	v_mfma_f32_16x16x32_bf16 v[118:121], v[166:169], v[184:187], v[118:121]
	v_mfma_f32_16x16x32_bf16 v[114:117], v[174:177], v[184:187], v[114:117]
	v_mfma_f32_16x16x32_bf16 v[102:105], v[166:169], v[196:199], v[102:105]
	v_mfma_f32_16x16x32_bf16 v[98:101], v[174:177], v[196:199], v[98:101]
	v_mfma_f32_16x16x32_bf16 v[86:89], v[166:169], v[214:217], v[86:89]
	v_mfma_f32_16x16x32_bf16 v[82:85], v[174:177], v[214:217], v[82:85]
	v_mfma_f32_16x16x32_bf16 v[70:73], v[166:169], v[222:225], v[70:73]
	v_mfma_f32_16x16x32_bf16 v[66:69], v[174:177], v[222:225], v[66:69]
	s_setprio 0
	s_barrier
	s_add_i32 s40, s51, s0
	v_lshl_add_u64 v[192:193], v[192:193], 0, s[22:23]
	s_mov_b32 m0, s40
	ds_read_b128 v[178:181], v148 offset:49152
	ds_read_b128 v[184:187], v148 offset:50176
	ds_read_b128 v[188:191], v148 offset:51200
	ds_read_b128 v[196:199], v148 offset:52224
	ds_read_b128 v[210:213], v148 offset:53248
	ds_read_b128 v[214:217], v148 offset:54272
	ds_read_b128 v[218:221], v148 offset:55296
	ds_read_b128 v[222:225], v148 offset:56320
	global_load_lds_dwordx4 v[192:193], off
	s_add_i32 m0, s40, 0x2000
	s_add_u32 s36, s36, 0x40080
	v_lshl_add_u64 v[192:193], v[202:203], 0, s[22:23]
	s_addc_u32 s37, s37, 0
	s_add_i32 s40, s52, s0
	global_load_lds_dwordx4 v[192:193], off
	v_lshl_add_u64 v[192:193], s[36:37], 0, v[0:1]
	s_mov_b32 m0, s40
	s_nop 0
	global_load_lds_dwordx4 v[192:193], off
	v_lshl_add_u64 v[192:193], s[36:37], 0, v[130:131]
	s_add_i32 m0, s40, 0x2000
	s_nop 0
	global_load_lds_dwordx4 v[192:193], off
	v_lshl_add_u64 v[192:193], v[226:227], 0, s[22:23]
	s_mov_b32 m0, s26
	s_nop 0
	global_load_lds_dwordx4 v[192:193], off
	v_lshl_add_u64 v[192:193], v[228:229], 0, s[22:23]
	s_mov_b32 m0, s28
	s_nop 0
	global_load_lds_dwordx4 v[192:193], off
	s_waitcnt vmcnt(8)
	s_waitcnt lgkmcnt(0)
	s_barrier
	s_setprio 1
	s_waitcnt lgkmcnt(0)
	v_mfma_f32_16x16x32_bf16 v[62:65], v[140:143], v[178:181], v[62:65]
	v_mfma_f32_16x16x32_bf16 v[58:61], v[154:157], v[178:181], v[58:61]
	v_mfma_f32_16x16x32_bf16 v[46:49], v[140:143], v[188:191], v[46:49]
	v_mfma_f32_16x16x32_bf16 v[42:45], v[154:157], v[188:191], v[42:45]
	v_mfma_f32_16x16x32_bf16 v[30:33], v[140:143], v[210:213], v[30:33]
	v_mfma_f32_16x16x32_bf16 v[26:29], v[154:157], v[210:213], v[26:29]
	v_mfma_f32_16x16x32_bf16 v[14:17], v[140:143], v[218:221], v[14:17]
	v_mfma_f32_16x16x32_bf16 v[10:13], v[154:157], v[218:221], v[10:13]
	v_mfma_f32_16x16x32_bf16 v[62:65], v[150:153], v[184:187], v[62:65]
	v_mfma_f32_16x16x32_bf16 v[58:61], v[158:161], v[184:187], v[58:61]
	v_mfma_f32_16x16x32_bf16 v[46:49], v[150:153], v[196:199], v[46:49]
	v_mfma_f32_16x16x32_bf16 v[42:45], v[158:161], v[196:199], v[42:45]
	v_mfma_f32_16x16x32_bf16 v[30:33], v[150:153], v[214:217], v[30:33]
	v_mfma_f32_16x16x32_bf16 v[26:29], v[158:161], v[214:217], v[26:29]
	v_mfma_f32_16x16x32_bf16 v[14:17], v[150:153], v[222:225], v[14:17]
	v_mfma_f32_16x16x32_bf16 v[10:13], v[158:161], v[222:225], v[10:13]
	s_setprio 0
	s_setprio 1
	v_mfma_f32_16x16x32_bf16 v[54:57], v[162:165], v[178:181], v[54:57]
	v_mfma_f32_16x16x32_bf16 v[50:53], v[170:173], v[178:181], v[50:53]
	v_mfma_f32_16x16x32_bf16 v[38:41], v[162:165], v[188:191], v[38:41]
	v_mfma_f32_16x16x32_bf16 v[34:37], v[170:173], v[188:191], v[34:37]
	v_mfma_f32_16x16x32_bf16 v[22:25], v[162:165], v[210:213], v[22:25]
	v_mfma_f32_16x16x32_bf16 v[18:21], v[170:173], v[210:213], v[18:21]
	v_mfma_f32_16x16x32_bf16 v[6:9], v[162:165], v[218:221], v[6:9]
	v_mfma_f32_16x16x32_bf16 v[2:5], v[170:173], v[218:221], v[2:5]
	v_mfma_f32_16x16x32_bf16 v[54:57], v[166:169], v[184:187], v[54:57]
	v_mfma_f32_16x16x32_bf16 v[50:53], v[174:177], v[184:187], v[50:53]
	v_mfma_f32_16x16x32_bf16 v[38:41], v[166:169], v[196:199], v[38:41]
	v_mfma_f32_16x16x32_bf16 v[34:37], v[174:177], v[196:199], v[34:37]
	v_mfma_f32_16x16x32_bf16 v[22:25], v[166:169], v[214:217], v[22:25]
	v_mfma_f32_16x16x32_bf16 v[18:21], v[174:177], v[214:217], v[18:21]
	v_mfma_f32_16x16x32_bf16 v[6:9], v[166:169], v[222:225], v[6:9]
	v_mfma_f32_16x16x32_bf16 v[2:5], v[174:177], v[222:225], v[2:5]
	s_setprio 0
	s_add_i32 s50, s50, 2
	s_add_u32 s34, s34, 0x100
	s_addc_u32 s35, s35, 0
	s_add_u32 s48, s48, 0x100
	s_addc_u32 s49, s49, 0
	s_cmp_gt_u32 s50, 13
	s_cbranch_scc1 .Lrot_exit_2
	s_add_u32 s36, s34, 0xfffc0080
	s_addc_u32 s37, s35, -1
	s_add_i32 s51, 0, 0x10000
	s_cmp_eq_u32 s50, 12
	s_cselect_b32 s41, s15, s37
	s_cselect_b32 s40, s46, s36
	v_add_u32_e32 v149, s51, v145
	s_cselect_b32 s37, s13, s49
	s_cselect_b32 s36, s47, s48
	s_add_i32 s54, 0, 0x14000
	s_barrier
	s_branch .Lrot_body_2
.Lrot_exit_2:
	s_barrier
	s_and_b64 vcc, exec, s[10:11]
	s_cbranch_vccz .LBB0_795
	s_barrier

.Lrot_body_3:
	ds_read_b128 v[140:143], v156
	ds_read_b128 v[148:151], v156 offset:1024
	ds_read_b128 v[152:155], v156 offset:2048
	ds_read_b128 v[156:159], v156 offset:3072
	ds_read_b128 v[160:163], v172
	ds_read_b128 v[164:167], v172 offset:1024
	ds_read_b128 v[168:171], v172 offset:2048
	ds_read_b128 v[172:175], v172 offset:3072
	v_lshl_add_u64 v[180:181], s[12:13], 0, v[136:137]
	s_add_i32 m0, s51, 0xc000
	ds_read_b128 v[176:179], v147
	ds_read_b128 v[184:187], v147 offset:1024
	ds_read_b128 v[188:191], v147 offset:2048
	ds_read_b128 v[196:199], v147 offset:3072
	ds_read_b128 v[210:213], v147 offset:4096
	ds_read_b128 v[214:217], v147 offset:5120
	ds_read_b128 v[218:221], v147 offset:6144
	ds_read_b128 v[222:225], v147 offset:7168
	global_load_lds_dwordx4 v[180:181], off
	v_lshl_add_u64 v[180:181], s[12:13], 0, v[138:139]
	s_add_i32 m0, s51, 0xe000
	s_nop 0
	global_load_lds_dwordx4 v[180:181], off
	s_waitcnt vmcnt(8)
	s_waitcnt lgkmcnt(0)
	s_barrier
	s_setprio 1
	s_waitcnt lgkmcnt(0)
	v_mfma_f32_16x16x32_bf16 v[126:129], v[140:143], v[176:179], v[126:129]
	v_mfma_f32_16x16x32_bf16 v[122:125], v[152:155], v[176:179], v[122:125]
	v_mfma_f32_16x16x32_bf16 v[110:113], v[140:143], v[188:191], v[110:113]
	v_mfma_f32_16x16x32_bf16 v[106:109], v[152:155], v[188:191], v[106:109]
	v_mfma_f32_16x16x32_bf16 v[94:97], v[140:143], v[210:213], v[94:97]
	v_mfma_f32_16x16x32_bf16 v[90:93], v[152:155], v[210:213], v[90:93]
	v_mfma_f32_16x16x32_bf16 v[78:81], v[140:143], v[218:221], v[78:81]
	v_mfma_f32_16x16x32_bf16 v[74:77], v[152:155], v[218:221], v[74:77]
	v_mfma_f32_16x16x32_bf16 v[126:129], v[148:151], v[184:187], v[126:129]
	v_mfma_f32_16x16x32_bf16 v[122:125], v[156:159], v[184:187], v[122:125]
	v_mfma_f32_16x16x32_bf16 v[110:113], v[148:151], v[196:199], v[110:113]
	v_mfma_f32_16x16x32_bf16 v[106:109], v[156:159], v[196:199], v[106:109]
	v_mfma_f32_16x16x32_bf16 v[94:97], v[148:151], v[214:217], v[94:97]
	v_mfma_f32_16x16x32_bf16 v[90:93], v[156:159], v[214:217], v[90:93]
	v_mfma_f32_16x16x32_bf16 v[78:81], v[148:151], v[222:225], v[78:81]
	v_mfma_f32_16x16x32_bf16 v[74:77], v[156:159], v[222:225], v[74:77]
	s_setprio 0
	s_setprio 1
	v_mfma_f32_16x16x32_bf16 v[118:121], v[160:163], v[176:179], v[118:121]
	v_mfma_f32_16x16x32_bf16 v[114:117], v[168:171], v[176:179], v[114:117]
	v_mfma_f32_16x16x32_bf16 v[102:105], v[160:163], v[188:191], v[102:105]
	v_mfma_f32_16x16x32_bf16 v[98:101], v[168:171], v[188:191], v[98:101]
	v_mfma_f32_16x16x32_bf16 v[86:89], v[160:163], v[210:213], v[86:89]
	v_mfma_f32_16x16x32_bf16 v[82:85], v[168:171], v[210:213], v[82:85]
	v_mfma_f32_16x16x32_bf16 v[70:73], v[160:163], v[218:221], v[70:73]
	v_mfma_f32_16x16x32_bf16 v[66:69], v[168:171], v[218:221], v[66:69]
	v_mfma_f32_16x16x32_bf16 v[118:121], v[164:167], v[184:187], v[118:121]
	v_mfma_f32_16x16x32_bf16 v[114:117], v[172:175], v[184:187], v[114:117]
	v_mfma_f32_16x16x32_bf16 v[102:105], v[164:167], v[196:199], v[102:105]
	v_mfma_f32_16x16x32_bf16 v[98:101], v[172:175], v[196:199], v[98:101]
	v_mfma_f32_16x16x32_bf16 v[86:89], v[164:167], v[214:217], v[86:89]
	v_mfma_f32_16x16x32_bf16 v[82:85], v[172:175], v[214:217], v[82:85]
	v_mfma_f32_16x16x32_bf16 v[70:73], v[164:167], v[222:225], v[70:73]
	v_mfma_f32_16x16x32_bf16 v[66:69], v[172:175], v[222:225], v[66:69]
	s_setprio 0
	s_barrier
	s_add_i32 s45, s45, s50
	v_lshl_add_u64 v[180:181], s[30:31], 0, v[0:1]
	s_mov_b32 m0, s45
	ds_read_b128 v[176:179], v147 offset:16384
	ds_read_b128 v[184:187], v147 offset:17408
	ds_read_b128 v[188:191], v147 offset:18432
	ds_read_b128 v[196:199], v147 offset:19456
	ds_read_b128 v[210:213], v147 offset:20480
	ds_read_b128 v[214:217], v147 offset:21504
	ds_read_b128 v[218:221], v147 offset:22528
	ds_read_b128 v[222:225], v147 offset:23552
	global_load_lds_dwordx4 v[180:181], off
	s_add_i32 m0, s45, 0x2000
	s_add_u32 s60, s30, 0x100000
	v_lshl_add_u64 v[192:193], s[30:31], 0, v[130:131]
	s_addc_u32 s61, s31, 0
	s_add_i32 s45, s59, s50
	global_load_lds_dwordx4 v[192:193], off
	v_lshl_add_u64 v[202:203], s[60:61], 0, v[0:1]
	s_mov_b32 m0, s45
	v_lshl_add_u64 v[226:227], s[36:37], 0, v[132:133]
	global_load_lds_dwordx4 v[202:203], off
	v_lshl_add_u64 v[202:203], s[60:61], 0, v[130:131]
	s_add_i32 m0, s45, 0x2000
	s_nop 0
	global_load_lds_dwordx4 v[202:203], off
	v_lshl_add_u64 v[202:203], s[36:37], 0, v[134:135]
	s_mov_b32 m0, s51
	s_nop 0
	global_load_lds_dwordx4 v[202:203], off
	s_mov_b32 m0, s52
	s_nop 0
	global_load_lds_dwordx4 v[226:227], off
	s_waitcnt vmcnt(8)
	s_waitcnt lgkmcnt(0)
	s_barrier
	s_setprio 1
	s_waitcnt lgkmcnt(0)
	v_mfma_f32_16x16x32_bf16 v[62:65], v[140:143], v[176:179], v[62:65]
	v_mfma_f32_16x16x32_bf16 v[58:61], v[152:155], v[176:179], v[58:61]
	v_mfma_f32_16x16x32_bf16 v[46:49], v[140:143], v[188:191], v[46:49]
	v_mfma_f32_16x16x32_bf16 v[42:45], v[152:155], v[188:191], v[42:45]
	v_mfma_f32_16x16x32_bf16 v[30:33], v[140:143], v[210:213], v[30:33]
	v_mfma_f32_16x16x32_bf16 v[26:29], v[152:155], v[210:213], v[26:29]
	v_mfma_f32_16x16x32_bf16 v[14:17], v[140:143], v[218:221], v[14:17]
	v_mfma_f32_16x16x32_bf16 v[10:13], v[152:155], v[218:221], v[10:13]
	v_mfma_f32_16x16x32_bf16 v[62:65], v[148:151], v[184:187], v[62:65]
	v_mfma_f32_16x16x32_bf16 v[58:61], v[156:159], v[184:187], v[58:61]
	v_mfma_f32_16x16x32_bf16 v[46:49], v[148:151], v[196:199], v[46:49]
	v_mfma_f32_16x16x32_bf16 v[42:45], v[156:159], v[196:199], v[42:45]
	v_mfma_f32_16x16x32_bf16 v[30:33], v[148:151], v[214:217], v[30:33]
	v_mfma_f32_16x16x32_bf16 v[26:29], v[156:159], v[214:217], v[26:29]
	v_mfma_f32_16x16x32_bf16 v[14:17], v[148:151], v[222:225], v[14:17]
	v_mfma_f32_16x16x32_bf16 v[10:13], v[156:159], v[222:225], v[10:13]
	s_setprio 0
	s_setprio 1
	v_mfma_f32_16x16x32_bf16 v[54:57], v[160:163], v[176:179], v[54:57]
	v_mfma_f32_16x16x32_bf16 v[50:53], v[168:171], v[176:179], v[50:53]
	v_mfma_f32_16x16x32_bf16 v[38:41], v[160:163], v[188:191], v[38:41]
	v_mfma_f32_16x16x32_bf16 v[34:37], v[168:171], v[188:191], v[34:37]
	v_mfma_f32_16x16x32_bf16 v[22:25], v[160:163], v[210:213], v[22:25]
	v_mfma_f32_16x16x32_bf16 v[18:21], v[168:171], v[210:213], v[18:21]
	v_mfma_f32_16x16x32_bf16 v[6:9], v[160:163], v[218:221], v[6:9]
	v_mfma_f32_16x16x32_bf16 v[2:5], v[168:171], v[218:221], v[2:5]
	v_mfma_f32_16x16x32_bf16 v[54:57], v[164:167], v[184:187], v[54:57]
	v_mfma_f32_16x16x32_bf16 v[50:53], v[172:175], v[184:187], v[50:53]
	v_mfma_f32_16x16x32_bf16 v[38:41], v[164:167], v[196:199], v[38:41]
	v_mfma_f32_16x16x32_bf16 v[34:37], v[172:175], v[196:199], v[34:37]
	v_mfma_f32_16x16x32_bf16 v[22:25], v[164:167], v[214:217], v[22:25]
	v_mfma_f32_16x16x32_bf16 v[18:21], v[172:175], v[214:217], v[18:21]
	v_mfma_f32_16x16x32_bf16 v[6:9], v[164:167], v[222:225], v[6:9]
	v_mfma_f32_16x16x32_bf16 v[2:5], v[172:175], v[222:225], v[2:5]
	s_setprio 0
	s_barrier
	s_add_i32 s45, 0, 0x18000
	s_add_i32 s59, 0, 0x1c000
	v_add_u32_e32 v156, s45, v145
	v_add_u32_e32 v172, s59, v145
	ds_read_b128 v[140:143], v156
	ds_read_b128 v[148:151], v156 offset:1024
	ds_read_b128 v[152:155], v156 offset:2048
	ds_read_b128 v[156:159], v156 offset:3072
	ds_read_b128 v[160:163], v172
	ds_read_b128 v[164:167], v172 offset:1024
	ds_read_b128 v[168:171], v172 offset:2048
	ds_read_b128 v[172:175], v172 offset:3072
	s_add_u32 s36, s36, 0x100000
	s_addc_u32 s37, s37, 0
	s_mov_b32 m0, s53
	v_lshl_add_u64 v[228:229], s[36:37], 0, v[134:135]
	ds_read_b128 v[176:179], v147 offset:32768
	ds_read_b128 v[184:187], v147 offset:33792
	ds_read_b128 v[188:191], v147 offset:34816
	ds_read_b128 v[196:199], v147 offset:35840
	ds_read_b128 v[210:213], v147 offset:36864
	ds_read_b128 v[214:217], v147 offset:37888
	ds_read_b128 v[218:221], v147 offset:38912
	ds_read_b128 v[222:225], v147 offset:39936
	global_load_lds_dwordx4 v[228:229], off
	v_lshl_add_u64 v[228:229], s[36:37], 0, v[132:133]
	s_mov_b32 m0, s54
	s_nop 0
	global_load_lds_dwordx4 v[228:229], off
	s_waitcnt vmcnt(8)
	s_waitcnt lgkmcnt(0)
	s_barrier
	s_setprio 1
	s_waitcnt lgkmcnt(0)
	v_mfma_f32_16x16x32_bf16 v[126:129], v[140:143], v[176:179], v[126:129]
	v_mfma_f32_16x16x32_bf16 v[122:125], v[152:155], v[176:179], v[122:125]
	v_mfma_f32_16x16x32_bf16 v[110:113], v[140:143], v[188:191], v[110:113]
	v_mfma_f32_16x16x32_bf16 v[106:109], v[152:155], v[188:191], v[106:109]
	v_mfma_f32_16x16x32_bf16 v[94:97], v[140:143], v[210:213], v[94:97]
	v_mfma_f32_16x16x32_bf16 v[90:93], v[152:155], v[210:213], v[90:93]
	v_mfma_f32_16x16x32_bf16 v[78:81], v[140:143], v[218:221], v[78:81]
	v_mfma_f32_16x16x32_bf16 v[74:77], v[152:155], v[218:221], v[74:77]
	v_mfma_f32_16x16x32_bf16 v[126:129], v[148:151], v[184:187], v[126:129]
	v_mfma_f32_16x16x32_bf16 v[122:125], v[156:159], v[184:187], v[122:125]
	v_mfma_f32_16x16x32_bf16 v[110:113], v[148:151], v[196:199], v[110:113]
	v_mfma_f32_16x16x32_bf16 v[106:109], v[156:159], v[196:199], v[106:109]
	v_mfma_f32_16x16x32_bf16 v[94:97], v[148:151], v[214:217], v[94:97]
	v_mfma_f32_16x16x32_bf16 v[90:93], v[156:159], v[214:217], v[90:93]
	v_mfma_f32_16x16x32_bf16 v[78:81], v[148:151], v[222:225], v[78:81]
	v_mfma_f32_16x16x32_bf16 v[74:77], v[156:159], v[222:225], v[74:77]
	s_setprio 0
	s_setprio 1
	v_mfma_f32_16x16x32_bf16 v[118:121], v[160:163], v[176:179], v[118:121]
	v_mfma_f32_16x16x32_bf16 v[114:117], v[168:171], v[176:179], v[114:117]
	v_mfma_f32_16x16x32_bf16 v[102:105], v[160:163], v[188:191], v[102:105]
	v_mfma_f32_16x16x32_bf16 v[98:101], v[168:171], v[188:191], v[98:101]
	v_mfma_f32_16x16x32_bf16 v[86:89], v[160:163], v[210:213], v[86:89]
	v_mfma_f32_16x16x32_bf16 v[82:85], v[168:171], v[210:213], v[82:85]
	v_mfma_f32_16x16x32_bf16 v[70:73], v[160:163], v[218:221], v[70:73]
	v_mfma_f32_16x16x32_bf16 v[66:69], v[168:171], v[218:221], v[66:69]
	v_mfma_f32_16x16x32_bf16 v[118:121], v[164:167], v[184:187], v[118:121]
	v_mfma_f32_16x16x32_bf16 v[114:117], v[172:175], v[184:187], v[114:117]
	v_mfma_f32_16x16x32_bf16 v[102:105], v[164:167], v[196:199], v[102:105]
	v_mfma_f32_16x16x32_bf16 v[98:101], v[172:175], v[196:199], v[98:101]
	v_mfma_f32_16x16x32_bf16 v[86:89], v[164:167], v[214:217], v[86:89]
	v_mfma_f32_16x16x32_bf16 v[82:85], v[172:175], v[214:217], v[82:85]
	v_mfma_f32_16x16x32_bf16 v[70:73], v[164:167], v[222:225], v[70:73]
	v_mfma_f32_16x16x32_bf16 v[66:69], v[172:175], v[222:225], v[66:69]
	s_setprio 0
	s_barrier
	s_add_i32 s36, s45, s50
	v_lshl_add_u64 v[180:181], v[180:181], 0, s[22:23]
	s_mov_b32 m0, s36
	ds_read_b128 v[176:179], v147 offset:49152
	ds_read_b128 v[184:187], v147 offset:50176
	ds_read_b128 v[188:191], v147 offset:51200
	ds_read_b128 v[196:199], v147 offset:52224
	ds_read_b128 v[210:213], v147 offset:53248
	ds_read_b128 v[214:217], v147 offset:54272
	ds_read_b128 v[218:221], v147 offset:55296
	ds_read_b128 v[222:225], v147 offset:56320
	global_load_lds_dwordx4 v[180:181], off
	s_add_i32 m0, s36, 0x2000
	s_add_u32 s30, s30, 0x100080
	v_lshl_add_u64 v[180:181], v[192:193], 0, s[22:23]
	s_addc_u32 s31, s31, 0
	s_add_i32 s36, s59, s50
	global_load_lds_dwordx4 v[180:181], off
	v_lshl_add_u64 v[180:181], s[30:31], 0, v[0:1]
	s_mov_b32 m0, s36
	s_nop 0
	global_load_lds_dwordx4 v[180:181], off
	v_lshl_add_u64 v[180:181], s[30:31], 0, v[130:131]
	s_add_i32 m0, s36, 0x2000
	s_nop 0
	global_load_lds_dwordx4 v[180:181], off
	v_lshl_add_u64 v[180:181], v[202:203], 0, s[22:23]
	s_mov_b32 m0, s56
	s_nop 0
	global_load_lds_dwordx4 v[180:181], off
	v_lshl_add_u64 v[180:181], v[226:227], 0, s[22:23]
	s_mov_b32 m0, s57
	s_nop 0
	global_load_lds_dwordx4 v[180:181], off
	s_waitcnt vmcnt(8)
	s_waitcnt lgkmcnt(0)
	s_barrier
	s_setprio 1
	s_waitcnt lgkmcnt(0)
	v_mfma_f32_16x16x32_bf16 v[62:65], v[140:143], v[176:179], v[62:65]
	v_mfma_f32_16x16x32_bf16 v[58:61], v[152:155], v[176:179], v[58:61]
	v_mfma_f32_16x16x32_bf16 v[46:49], v[140:143], v[188:191], v[46:49]
	v_mfma_f32_16x16x32_bf16 v[42:45], v[152:155], v[188:191], v[42:45]
	v_mfma_f32_16x16x32_bf16 v[30:33], v[140:143], v[210:213], v[30:33]
	v_mfma_f32_16x16x32_bf16 v[26:29], v[152:155], v[210:213], v[26:29]
	v_mfma_f32_16x16x32_bf16 v[14:17], v[140:143], v[218:221], v[14:17]
	v_mfma_f32_16x16x32_bf16 v[10:13], v[152:155], v[218:221], v[10:13]
	v_mfma_f32_16x16x32_bf16 v[62:65], v[148:151], v[184:187], v[62:65]
	v_mfma_f32_16x16x32_bf16 v[58:61], v[156:159], v[184:187], v[58:61]
	v_mfma_f32_16x16x32_bf16 v[46:49], v[148:151], v[196:199], v[46:49]
	v_mfma_f32_16x16x32_bf16 v[42:45], v[156:159], v[196:199], v[42:45]
	v_mfma_f32_16x16x32_bf16 v[30:33], v[148:151], v[214:217], v[30:33]
	v_mfma_f32_16x16x32_bf16 v[26:29], v[156:159], v[214:217], v[26:29]
	v_mfma_f32_16x16x32_bf16 v[14:17], v[148:151], v[222:225], v[14:17]
	v_mfma_f32_16x16x32_bf16 v[10:13], v[156:159], v[222:225], v[10:13]
	s_setprio 0
	s_setprio 1
	v_mfma_f32_16x16x32_bf16 v[54:57], v[160:163], v[176:179], v[54:57]
	v_mfma_f32_16x16x32_bf16 v[50:53], v[168:171], v[176:179], v[50:53]
	v_mfma_f32_16x16x32_bf16 v[38:41], v[160:163], v[188:191], v[38:41]
	v_mfma_f32_16x16x32_bf16 v[34:37], v[168:171], v[188:191], v[34:37]
	v_mfma_f32_16x16x32_bf16 v[22:25], v[160:163], v[210:213], v[22:25]
	v_mfma_f32_16x16x32_bf16 v[18:21], v[168:171], v[210:213], v[18:21]
	v_mfma_f32_16x16x32_bf16 v[6:9], v[160:163], v[218:221], v[6:9]
	v_mfma_f32_16x16x32_bf16 v[2:5], v[168:171], v[218:221], v[2:5]
	v_mfma_f32_16x16x32_bf16 v[54:57], v[164:167], v[184:187], v[54:57]
	v_mfma_f32_16x16x32_bf16 v[50:53], v[172:175], v[184:187], v[50:53]
	v_mfma_f32_16x16x32_bf16 v[38:41], v[164:167], v[196:199], v[38:41]
	v_mfma_f32_16x16x32_bf16 v[34:37], v[172:175], v[196:199], v[34:37]
	v_mfma_f32_16x16x32_bf16 v[22:25], v[164:167], v[214:217], v[22:25]
	v_mfma_f32_16x16x32_bf16 v[18:21], v[172:175], v[214:217], v[18:21]
	v_mfma_f32_16x16x32_bf16 v[6:9], v[164:167], v[222:225], v[6:9]
	v_mfma_f32_16x16x32_bf16 v[2:5], v[172:175], v[222:225], v[2:5]
	s_setprio 0
	s_add_i32 s35, s35, 2
	s_add_u32 s12, s12, 0x100
	s_addc_u32 s13, s13, 0
	s_add_u32 s26, s26, 0x100
	s_addc_u32 s28, s28, 0
	s_cmp_gt_u32 s35, 61
	s_cbranch_scc1 .Lrot_exit_3
	s_add_u32 s30, s12, 0xfff00080
	s_addc_u32 s31, s13, -1
	s_add_i32 s45, 0, 0x10000
	s_cmp_eq_u32 s35, 60
	s_cselect_b32 s37, s3, s31
	s_cselect_b32 s36, s16, s30
	s_cselect_b32 s31, s24, s28
	s_cselect_b32 s30, s25, s26
	s_add_i32 s59, 0, 0x14000
	v_add_u32_e32 v156, s45, v145
	v_add_u32_e32 v172, s59, v145
	s_barrier
	s_branch .Lrot_body_3

.Lrot_body_4:
	ds_read_b128 v[142:145], v154
	ds_read_b128 v[146:149], v154 offset:1024
	ds_read_b128 v[150:153], v154 offset:2048
	ds_read_b128 v[154:157], v154 offset:3072
	ds_read_b128 v[158:161], v170
	ds_read_b128 v[162:165], v170 offset:1024
	ds_read_b128 v[166:169], v170 offset:2048
	ds_read_b128 v[170:173], v170 offset:3072
	v_lshl_add_u64 v[192:193], s[36:37], 0, v[136:137]
	s_add_i32 m0, s18, 0xc000
	ds_read_b128 v[174:177], v141
	ds_read_b128 v[178:181], v141 offset:1024
	ds_read_b128 v[184:187], v141 offset:2048
	ds_read_b128 v[188:191], v141 offset:3072
	ds_read_b128 v[196:199], v141 offset:4096
	ds_read_b128 v[210:213], v141 offset:5120
	ds_read_b128 v[214:217], v141 offset:6144
	ds_read_b128 v[218:221], v141 offset:7168
	global_load_lds_dwordx4 v[192:193], off
	v_lshl_add_u64 v[192:193], s[36:37], 0, v[138:139]
	s_add_i32 m0, s18, 0xe000
	s_nop 0
	global_load_lds_dwordx4 v[192:193], off
	s_waitcnt vmcnt(8)
	s_waitcnt lgkmcnt(0)
	s_barrier
	s_setprio 1
	s_waitcnt lgkmcnt(0)
	v_mfma_f32_16x16x32_bf16 v[122:125], v[142:145], v[174:177], v[122:125]
	v_mfma_f32_16x16x32_bf16 v[126:129], v[150:153], v[174:177], v[126:129]
	v_mfma_f32_16x16x32_bf16 v[110:113], v[142:145], v[184:187], v[110:113]
	v_mfma_f32_16x16x32_bf16 v[106:109], v[150:153], v[184:187], v[106:109]
	v_mfma_f32_16x16x32_bf16 v[94:97], v[142:145], v[196:199], v[94:97]
	v_mfma_f32_16x16x32_bf16 v[90:93], v[150:153], v[196:199], v[90:93]
	v_mfma_f32_16x16x32_bf16 v[78:81], v[142:145], v[214:217], v[78:81]
	v_mfma_f32_16x16x32_bf16 v[74:77], v[150:153], v[214:217], v[74:77]
	v_mfma_f32_16x16x32_bf16 v[122:125], v[146:149], v[178:181], v[122:125]
	v_mfma_f32_16x16x32_bf16 v[126:129], v[154:157], v[178:181], v[126:129]
	v_mfma_f32_16x16x32_bf16 v[110:113], v[146:149], v[188:191], v[110:113]
	v_mfma_f32_16x16x32_bf16 v[106:109], v[154:157], v[188:191], v[106:109]
	v_mfma_f32_16x16x32_bf16 v[94:97], v[146:149], v[210:213], v[94:97]
	v_mfma_f32_16x16x32_bf16 v[90:93], v[154:157], v[210:213], v[90:93]
	v_mfma_f32_16x16x32_bf16 v[78:81], v[146:149], v[218:221], v[78:81]
	v_mfma_f32_16x16x32_bf16 v[74:77], v[154:157], v[218:221], v[74:77]
	s_setprio 0
	s_setprio 1
	v_mfma_f32_16x16x32_bf16 v[118:121], v[158:161], v[174:177], v[118:121]
	v_mfma_f32_16x16x32_bf16 v[114:117], v[166:169], v[174:177], v[114:117]
	v_mfma_f32_16x16x32_bf16 v[102:105], v[158:161], v[184:187], v[102:105]
	v_mfma_f32_16x16x32_bf16 v[98:101], v[166:169], v[184:187], v[98:101]
	v_mfma_f32_16x16x32_bf16 v[86:89], v[158:161], v[196:199], v[86:89]
	v_mfma_f32_16x16x32_bf16 v[82:85], v[166:169], v[196:199], v[82:85]
	v_mfma_f32_16x16x32_bf16 v[70:73], v[158:161], v[214:217], v[70:73]
	v_mfma_f32_16x16x32_bf16 v[66:69], v[166:169], v[214:217], v[66:69]
	v_mfma_f32_16x16x32_bf16 v[118:121], v[162:165], v[178:181], v[118:121]
	v_mfma_f32_16x16x32_bf16 v[114:117], v[170:173], v[178:181], v[114:117]
	v_mfma_f32_16x16x32_bf16 v[102:105], v[162:165], v[188:191], v[102:105]
	v_mfma_f32_16x16x32_bf16 v[98:101], v[170:173], v[188:191], v[98:101]
	v_mfma_f32_16x16x32_bf16 v[86:89], v[162:165], v[210:213], v[86:89]
	v_mfma_f32_16x16x32_bf16 v[82:85], v[170:173], v[210:213], v[82:85]
	v_mfma_f32_16x16x32_bf16 v[70:73], v[162:165], v[218:221], v[70:73]
	v_mfma_f32_16x16x32_bf16 v[66:69], v[170:173], v[218:221], v[66:69]
	s_setprio 0
	s_barrier
	s_add_i32 s56, s56, s17
	v_lshl_add_u64 v[192:193], s[54:55], 0, v[0:1]
	s_mov_b32 m0, s56
	ds_read_b128 v[174:177], v141 offset:16384
	ds_read_b128 v[178:181], v141 offset:17408
	ds_read_b128 v[184:187], v141 offset:18432
	ds_read_b128 v[188:191], v141 offset:19456
	ds_read_b128 v[196:199], v141 offset:20480
	ds_read_b128 v[210:213], v141 offset:21504
	ds_read_b128 v[214:217], v141 offset:22528
	ds_read_b128 v[218:221], v141 offset:23552
	global_load_lds_dwordx4 v[192:193], off
	s_add_i32 m0, s56, 0x2000
	v_lshl_add_u64 v[202:203], s[54:55], 0, v[130:131]
	s_add_u32 s54, s54, s10
	s_addc_u32 s55, s55, s11
	s_add_i32 s53, s53, s17
	global_load_lds_dwordx4 v[202:203], off
	v_lshl_add_u64 v[222:223], s[54:55], 0, v[0:1]
	s_mov_b32 m0, s53
	v_lshl_add_u64 v[224:225], s[54:55], 0, v[130:131]
	global_load_lds_dwordx4 v[222:223], off
	s_add_i32 m0, s53, 0x2000
	v_lshl_add_u64 v[226:227], s[40:41], 0, v[134:135]
	global_load_lds_dwordx4 v[224:225], off
	s_mov_b32 m0, s18
	v_lshl_add_u64 v[228:229], s[40:41], 0, v[132:133]
	global_load_lds_dwordx4 v[226:227], off
	s_mov_b32 m0, s19
	s_nop 0
	global_load_lds_dwordx4 v[228:229], off
	s_waitcnt vmcnt(8)
	s_waitcnt lgkmcnt(0)
	s_barrier
	s_setprio 1
	s_waitcnt lgkmcnt(0)
	v_mfma_f32_16x16x32_bf16 v[62:65], v[142:145], v[174:177], v[62:65]
	v_mfma_f32_16x16x32_bf16 v[58:61], v[150:153], v[174:177], v[58:61]
	v_mfma_f32_16x16x32_bf16 v[46:49], v[142:145], v[184:187], v[46:49]
	v_mfma_f32_16x16x32_bf16 v[42:45], v[150:153], v[184:187], v[42:45]
	v_mfma_f32_16x16x32_bf16 v[30:33], v[142:145], v[196:199], v[30:33]
	v_mfma_f32_16x16x32_bf16 v[26:29], v[150:153], v[196:199], v[26:29]
	v_mfma_f32_16x16x32_bf16 v[14:17], v[142:145], v[214:217], v[14:17]
	v_mfma_f32_16x16x32_bf16 v[10:13], v[150:153], v[214:217], v[10:13]
	v_mfma_f32_16x16x32_bf16 v[62:65], v[146:149], v[178:181], v[62:65]
	v_mfma_f32_16x16x32_bf16 v[58:61], v[154:157], v[178:181], v[58:61]
	v_mfma_f32_16x16x32_bf16 v[46:49], v[146:149], v[188:191], v[46:49]
	v_mfma_f32_16x16x32_bf16 v[42:45], v[154:157], v[188:191], v[42:45]
	v_mfma_f32_16x16x32_bf16 v[30:33], v[146:149], v[210:213], v[30:33]
	v_mfma_f32_16x16x32_bf16 v[26:29], v[154:157], v[210:213], v[26:29]
	v_mfma_f32_16x16x32_bf16 v[14:17], v[146:149], v[218:221], v[14:17]
	v_mfma_f32_16x16x32_bf16 v[10:13], v[154:157], v[218:221], v[10:13]
	s_setprio 0
	s_setprio 1
	v_mfma_f32_16x16x32_bf16 v[54:57], v[158:161], v[174:177], v[54:57]
	v_mfma_f32_16x16x32_bf16 v[50:53], v[166:169], v[174:177], v[50:53]
	v_mfma_f32_16x16x32_bf16 v[38:41], v[158:161], v[184:187], v[38:41]
	v_mfma_f32_16x16x32_bf16 v[34:37], v[166:169], v[184:187], v[34:37]
	v_mfma_f32_16x16x32_bf16 v[22:25], v[158:161], v[196:199], v[22:25]
	v_mfma_f32_16x16x32_bf16 v[18:21], v[166:169], v[196:199], v[18:21]
	v_mfma_f32_16x16x32_bf16 v[6:9], v[158:161], v[214:217], v[6:9]
	v_mfma_f32_16x16x32_bf16 v[2:5], v[166:169], v[214:217], v[2:5]
	v_mfma_f32_16x16x32_bf16 v[54:57], v[162:165], v[178:181], v[54:57]
	v_mfma_f32_16x16x32_bf16 v[50:53], v[170:173], v[178:181], v[50:53]
	v_mfma_f32_16x16x32_bf16 v[38:41], v[162:165], v[188:191], v[38:41]
	v_mfma_f32_16x16x32_bf16 v[34:37], v[170:173], v[188:191], v[34:37]
	v_mfma_f32_16x16x32_bf16 v[22:25], v[162:165], v[210:213], v[22:25]
	v_mfma_f32_16x16x32_bf16 v[18:21], v[170:173], v[210:213], v[18:21]
	v_mfma_f32_16x16x32_bf16 v[6:9], v[162:165], v[218:221], v[6:9]
	v_mfma_f32_16x16x32_bf16 v[2:5], v[170:173], v[218:221], v[2:5]
	s_setprio 0
	s_barrier
	s_add_i32 s53, 0, 0x18000
	s_add_i32 s54, 0, 0x1c000
	v_add_u32_e32 v154, s53, v140
	v_add_u32_e32 v170, s54, v140
	ds_read_b128 v[142:145], v154
	ds_read_b128 v[146:149], v154 offset:1024
	ds_read_b128 v[150:153], v154 offset:2048
	ds_read_b128 v[154:157], v154 offset:3072
	ds_read_b128 v[158:161], v170
	ds_read_b128 v[162:165], v170 offset:1024
	ds_read_b128 v[166:169], v170 offset:2048
	ds_read_b128 v[170:173], v170 offset:3072
	s_add_u32 s40, s40, s10
	s_addc_u32 s41, s41, s11
	s_mov_b32 m0, s24
	v_lshl_add_u64 v[230:231], s[40:41], 0, v[134:135]
	ds_read_b128 v[174:177], v141 offset:32768
	ds_read_b128 v[178:181], v141 offset:33792
	ds_read_b128 v[184:187], v141 offset:34816
	ds_read_b128 v[188:191], v141 offset:35840
	ds_read_b128 v[196:199], v141 offset:36864
	ds_read_b128 v[210:213], v141 offset:37888
	ds_read_b128 v[214:217], v141 offset:38912
	ds_read_b128 v[218:221], v141 offset:39936
	global_load_lds_dwordx4 v[230:231], off
	v_lshl_add_u64 v[230:231], s[40:41], 0, v[132:133]
	s_mov_b32 m0, s25
	s_nop 0
	global_load_lds_dwordx4 v[230:231], off
	s_waitcnt vmcnt(8)
	s_waitcnt lgkmcnt(0)
	s_barrier
	s_setprio 1
	s_waitcnt lgkmcnt(0)
	v_mfma_f32_16x16x32_bf16 v[122:125], v[142:145], v[174:177], v[122:125]
	v_mfma_f32_16x16x32_bf16 v[126:129], v[150:153], v[174:177], v[126:129]
	v_mfma_f32_16x16x32_bf16 v[110:113], v[142:145], v[184:187], v[110:113]
	v_mfma_f32_16x16x32_bf16 v[106:109], v[150:153], v[184:187], v[106:109]
	v_mfma_f32_16x16x32_bf16 v[94:97], v[142:145], v[196:199], v[94:97]
	v_mfma_f32_16x16x32_bf16 v[90:93], v[150:153], v[196:199], v[90:93]
	v_mfma_f32_16x16x32_bf16 v[78:81], v[142:145], v[214:217], v[78:81]
	v_mfma_f32_16x16x32_bf16 v[74:77], v[150:153], v[214:217], v[74:77]
	v_mfma_f32_16x16x32_bf16 v[122:125], v[146:149], v[178:181], v[122:125]
	v_mfma_f32_16x16x32_bf16 v[126:129], v[154:157], v[178:181], v[126:129]
	v_mfma_f32_16x16x32_bf16 v[110:113], v[146:149], v[188:191], v[110:113]
	v_mfma_f32_16x16x32_bf16 v[106:109], v[154:157], v[188:191], v[106:109]
	v_mfma_f32_16x16x32_bf16 v[94:97], v[146:149], v[210:213], v[94:97]
	v_mfma_f32_16x16x32_bf16 v[90:93], v[154:157], v[210:213], v[90:93]
	v_mfma_f32_16x16x32_bf16 v[78:81], v[146:149], v[218:221], v[78:81]
	v_mfma_f32_16x16x32_bf16 v[74:77], v[154:157], v[218:221], v[74:77]
	s_setprio 0
	s_setprio 1
	v_mfma_f32_16x16x32_bf16 v[118:121], v[158:161], v[174:177], v[118:121]
	v_mfma_f32_16x16x32_bf16 v[114:117], v[166:169], v[174:177], v[114:117]
	v_mfma_f32_16x16x32_bf16 v[102:105], v[158:161], v[184:187], v[102:105]
	v_mfma_f32_16x16x32_bf16 v[98:101], v[166:169], v[184:187], v[98:101]
	v_mfma_f32_16x16x32_bf16 v[86:89], v[158:161], v[196:199], v[86:89]
	v_mfma_f32_16x16x32_bf16 v[82:85], v[166:169], v[196:199], v[82:85]
	v_mfma_f32_16x16x32_bf16 v[70:73], v[158:161], v[214:217], v[70:73]
	v_mfma_f32_16x16x32_bf16 v[66:69], v[166:169], v[214:217], v[66:69]
	v_mfma_f32_16x16x32_bf16 v[118:121], v[162:165], v[178:181], v[118:121]
	v_mfma_f32_16x16x32_bf16 v[114:117], v[170:173], v[178:181], v[114:117]
	v_mfma_f32_16x16x32_bf16 v[102:105], v[162:165], v[188:191], v[102:105]
	v_mfma_f32_16x16x32_bf16 v[98:101], v[170:173], v[188:191], v[98:101]
	v_mfma_f32_16x16x32_bf16 v[86:89], v[162:165], v[210:213], v[86:89]
	v_mfma_f32_16x16x32_bf16 v[82:85], v[170:173], v[210:213], v[82:85]
	v_mfma_f32_16x16x32_bf16 v[70:73], v[162:165], v[218:221], v[70:73]
	v_mfma_f32_16x16x32_bf16 v[66:69], v[170:173], v[218:221], v[66:69]
	s_setprio 0
	s_barrier
	s_add_i32 s40, s53, s17
	v_lshl_add_u64 v[192:193], v[192:193], 0, s[22:23]
	s_mov_b32 m0, s40
	ds_read_b128 v[174:177], v141 offset:49152
	ds_read_b128 v[178:181], v141 offset:50176
	ds_read_b128 v[184:187], v141 offset:51200
	ds_read_b128 v[188:191], v141 offset:52224
	ds_read_b128 v[196:199], v141 offset:53248
	ds_read_b128 v[210:213], v141 offset:54272
	ds_read_b128 v[214:217], v141 offset:55296
	ds_read_b128 v[218:221], v141 offset:56320
	global_load_lds_dwordx4 v[192:193], off
	v_lshl_add_u64 v[192:193], v[202:203], 0, s[22:23]
	s_add_i32 m0, s40, 0x2000
	s_add_i32 s40, s54, s17
	global_load_lds_dwordx4 v[192:193], off
	v_lshl_add_u64 v[192:193], v[222:223], 0, s[22:23]
	s_mov_b32 m0, s40
	s_nop 0
	global_load_lds_dwordx4 v[192:193], off
	v_lshl_add_u64 v[192:193], v[224:225], 0, s[22:23]
	s_add_i32 m0, s40, 0x2000
	s_nop 0
	global_load_lds_dwordx4 v[192:193], off
	v_lshl_add_u64 v[192:193], v[226:227], 0, s[22:23]
	s_mov_b32 m0, s42
	s_nop 0
	global_load_lds_dwordx4 v[192:193], off
	v_lshl_add_u64 v[192:193], v[228:229], 0, s[22:23]
	s_mov_b32 m0, s43
	s_nop 0
	global_load_lds_dwordx4 v[192:193], off
	s_waitcnt vmcnt(8)
	s_waitcnt lgkmcnt(0)
	s_barrier
	s_setprio 1
	s_waitcnt lgkmcnt(0)
	v_mfma_f32_16x16x32_bf16 v[62:65], v[142:145], v[174:177], v[62:65]
	v_mfma_f32_16x16x32_bf16 v[58:61], v[150:153], v[174:177], v[58:61]
	v_mfma_f32_16x16x32_bf16 v[46:49], v[142:145], v[184:187], v[46:49]
	v_mfma_f32_16x16x32_bf16 v[42:45], v[150:153], v[184:187], v[42:45]
	v_mfma_f32_16x16x32_bf16 v[30:33], v[142:145], v[196:199], v[30:33]
	v_mfma_f32_16x16x32_bf16 v[26:29], v[150:153], v[196:199], v[26:29]
	v_mfma_f32_16x16x32_bf16 v[14:17], v[142:145], v[214:217], v[14:17]
	v_mfma_f32_16x16x32_bf16 v[10:13], v[150:153], v[214:217], v[10:13]
	v_mfma_f32_16x16x32_bf16 v[62:65], v[146:149], v[178:181], v[62:65]
	v_mfma_f32_16x16x32_bf16 v[58:61], v[154:157], v[178:181], v[58:61]
	v_mfma_f32_16x16x32_bf16 v[46:49], v[146:149], v[188:191], v[46:49]
	v_mfma_f32_16x16x32_bf16 v[42:45], v[154:157], v[188:191], v[42:45]
	v_mfma_f32_16x16x32_bf16 v[30:33], v[146:149], v[210:213], v[30:33]
	v_mfma_f32_16x16x32_bf16 v[26:29], v[154:157], v[210:213], v[26:29]
	v_mfma_f32_16x16x32_bf16 v[14:17], v[146:149], v[218:221], v[14:17]
	v_mfma_f32_16x16x32_bf16 v[10:13], v[154:157], v[218:221], v[10:13]
	s_setprio 0
	s_setprio 1
	v_mfma_f32_16x16x32_bf16 v[54:57], v[158:161], v[174:177], v[54:57]
	v_mfma_f32_16x16x32_bf16 v[50:53], v[166:169], v[174:177], v[50:53]
	v_mfma_f32_16x16x32_bf16 v[38:41], v[158:161], v[184:187], v[38:41]
	v_mfma_f32_16x16x32_bf16 v[34:37], v[166:169], v[184:187], v[34:37]
	v_mfma_f32_16x16x32_bf16 v[22:25], v[158:161], v[196:199], v[22:25]
	v_mfma_f32_16x16x32_bf16 v[18:21], v[166:169], v[196:199], v[18:21]
	v_mfma_f32_16x16x32_bf16 v[6:9], v[158:161], v[214:217], v[6:9]
	v_mfma_f32_16x16x32_bf16 v[2:5], v[166:169], v[214:217], v[2:5]
	v_mfma_f32_16x16x32_bf16 v[54:57], v[162:165], v[178:181], v[54:57]
	v_mfma_f32_16x16x32_bf16 v[50:53], v[170:173], v[178:181], v[50:53]
	v_mfma_f32_16x16x32_bf16 v[38:41], v[162:165], v[188:191], v[38:41]
	v_mfma_f32_16x16x32_bf16 v[34:37], v[170:173], v[188:191], v[34:37]
	v_mfma_f32_16x16x32_bf16 v[22:25], v[162:165], v[210:213], v[22:25]
	v_mfma_f32_16x16x32_bf16 v[18:21], v[170:173], v[210:213], v[18:21]
	v_mfma_f32_16x16x32_bf16 v[6:9], v[162:165], v[218:221], v[6:9]
	v_mfma_f32_16x16x32_bf16 v[2:5], v[170:173], v[218:221], v[2:5]
	s_setprio 0
	s_add_u32 s36, s36, 0x100
	s_addc_u32 s37, s37, 0
	s_add_u32 s50, s50, 0x100
	s_addc_u32 s51, s51, 0
	s_cmp_ge_i32 s52, s29
	s_mov_b32 s40, s52
	s_cbranch_scc1 .Lrot_exit_4
	s_add_i32 s52, s40, 2
	s_add_u32 s53, s36, 0x80
	s_addc_u32 s41, s37, 0
	s_add_i32 s56, 0, 0x10000
	s_cmp_eq_u32 s44, s40
	s_cselect_b32 s41, s7, s41
	s_cselect_b32 s40, s6, s53
	s_cselect_b32 s55, s35, s51
	s_cselect_b32 s54, s34, s50
	s_add_i32 s53, 0, 0x14000
	v_add_u32_e32 v154, s56, v140
	v_add_u32_e32 v170, s53, v140
	s_barrier
	s_branch .Lrot_body_4
.Lrot_exit_4:
	s_barrier

.Lrot_body_5:
	ds_read_b128 v[140:143], v144
	ds_read_b128 v[152:155], v144 offset:1024
	ds_read_b128 v[156:159], v144 offset:2048
	ds_read_b128 v[160:163], v144 offset:3072
	v_add_u32_e32 v144, s25, v147
	ds_read_b128 v[164:167], v144
	ds_read_b128 v[168:171], v144 offset:1024
	ds_read_b128 v[172:175], v144 offset:2048
	ds_read_b128 v[176:179], v144 offset:3072
	v_lshl_add_u64 v[144:145], s[12:13], 0, v[136:137]
	s_add_i32 m0, s47, 0xc000
	ds_read_b128 v[184:187], v150
	ds_read_b128 v[188:191], v150 offset:1024
	ds_read_b128 v[196:199], v150 offset:2048
	ds_read_b128 v[210:213], v150 offset:3072
	ds_read_b128 v[214:217], v150 offset:4096
	ds_read_b128 v[218:221], v150 offset:5120
	ds_read_b128 v[222:225], v150 offset:6144
	ds_read_b128 v[226:229], v150 offset:7168
	global_load_lds_dwordx4 v[144:145], off
	v_lshl_add_u64 v[144:145], s[12:13], 0, v[138:139]
	s_add_i32 m0, s47, 0xe000
	s_nop 0
	global_load_lds_dwordx4 v[144:145], off
	s_waitcnt vmcnt(8)
	s_waitcnt lgkmcnt(0)
	s_barrier
	s_setprio 1
	s_waitcnt lgkmcnt(0)
	v_mfma_f32_16x16x32_bf16 v[126:129], v[140:143], v[184:187], v[126:129]
	v_mfma_f32_16x16x32_bf16 v[122:125], v[156:159], v[184:187], v[122:125]
	v_mfma_f32_16x16x32_bf16 v[110:113], v[140:143], v[196:199], v[110:113]
	v_mfma_f32_16x16x32_bf16 v[106:109], v[156:159], v[196:199], v[106:109]
	v_mfma_f32_16x16x32_bf16 v[94:97], v[140:143], v[214:217], v[94:97]
	v_mfma_f32_16x16x32_bf16 v[90:93], v[156:159], v[214:217], v[90:93]
	v_mfma_f32_16x16x32_bf16 v[78:81], v[140:143], v[222:225], v[78:81]
	v_mfma_f32_16x16x32_bf16 v[74:77], v[156:159], v[222:225], v[74:77]
	v_mfma_f32_16x16x32_bf16 v[126:129], v[152:155], v[188:191], v[126:129]
	v_mfma_f32_16x16x32_bf16 v[122:125], v[160:163], v[188:191], v[122:125]
	v_mfma_f32_16x16x32_bf16 v[110:113], v[152:155], v[210:213], v[110:113]
	v_mfma_f32_16x16x32_bf16 v[106:109], v[160:163], v[210:213], v[106:109]
	v_mfma_f32_16x16x32_bf16 v[94:97], v[152:155], v[218:221], v[94:97]
	v_mfma_f32_16x16x32_bf16 v[90:93], v[160:163], v[218:221], v[90:93]
	v_mfma_f32_16x16x32_bf16 v[78:81], v[152:155], v[226:229], v[78:81]
	v_mfma_f32_16x16x32_bf16 v[74:77], v[160:163], v[226:229], v[74:77]
	s_setprio 0
	s_setprio 1
	v_mfma_f32_16x16x32_bf16 v[118:121], v[164:167], v[184:187], v[118:121]
	v_mfma_f32_16x16x32_bf16 v[114:117], v[172:175], v[184:187], v[114:117]
	v_mfma_f32_16x16x32_bf16 v[102:105], v[164:167], v[196:199], v[102:105]
	v_mfma_f32_16x16x32_bf16 v[98:101], v[172:175], v[196:199], v[98:101]
	v_mfma_f32_16x16x32_bf16 v[86:89], v[164:167], v[214:217], v[86:89]
	v_mfma_f32_16x16x32_bf16 v[82:85], v[172:175], v[214:217], v[82:85]
	v_mfma_f32_16x16x32_bf16 v[70:73], v[164:167], v[222:225], v[70:73]
	v_mfma_f32_16x16x32_bf16 v[66:69], v[172:175], v[222:225], v[66:69]
	v_mfma_f32_16x16x32_bf16 v[118:121], v[168:171], v[188:191], v[118:121]
	v_mfma_f32_16x16x32_bf16 v[114:117], v[176:179], v[188:191], v[114:117]
	v_mfma_f32_16x16x32_bf16 v[102:105], v[168:171], v[210:213], v[102:105]
	v_mfma_f32_16x16x32_bf16 v[98:101], v[176:179], v[210:213], v[98:101]
	v_mfma_f32_16x16x32_bf16 v[86:89], v[168:171], v[218:221], v[86:89]
	v_mfma_f32_16x16x32_bf16 v[82:85], v[176:179], v[218:221], v[82:85]
	v_mfma_f32_16x16x32_bf16 v[70:73], v[168:171], v[226:229], v[70:73]
	v_mfma_f32_16x16x32_bf16 v[66:69], v[176:179], v[226:229], v[66:69]
	s_setprio 0
	s_barrier
	s_add_i32 s26, s28, s17
	v_lshl_add_u64 v[144:145], s[30:31], 0, v[0:1]
	s_mov_b32 m0, s26
	ds_read_b128 v[184:187], v150 offset:16384
	ds_read_b128 v[188:191], v150 offset:17408
	ds_read_b128 v[196:199], v150 offset:18432
	ds_read_b128 v[210:213], v150 offset:19456
	ds_read_b128 v[214:217], v150 offset:20480
	ds_read_b128 v[218:221], v150 offset:21504
	ds_read_b128 v[222:225], v150 offset:22528
	ds_read_b128 v[226:229], v150 offset:23552
	global_load_lds_dwordx4 v[144:145], off
	s_add_i32 m0, s26, 0x2000
	s_add_u32 s60, s30, 0x40000
	v_lshl_add_u64 v[180:181], s[30:31], 0, v[130:131]
	s_addc_u32 s61, s31, 0
	s_add_i32 s25, s25, s17
	global_load_lds_dwordx4 v[180:181], off
	v_lshl_add_u64 v[192:193], s[60:61], 0, v[0:1]
	s_mov_b32 m0, s25
	v_lshl_add_u64 v[202:203], s[36:37], 0, v[132:133]
	global_load_lds_dwordx4 v[192:193], off
	v_lshl_add_u64 v[192:193], s[60:61], 0, v[130:131]
	s_add_i32 m0, s25, 0x2000
	s_nop 0
	global_load_lds_dwordx4 v[192:193], off
	v_lshl_add_u64 v[192:193], s[36:37], 0, v[134:135]
	s_mov_b32 m0, s47
	s_nop 0
	global_load_lds_dwordx4 v[192:193], off
	s_mov_b32 m0, s48
	s_nop 0
	global_load_lds_dwordx4 v[202:203], off
	s_waitcnt vmcnt(8)
	s_waitcnt lgkmcnt(0)
	s_barrier
	s_setprio 1
	s_waitcnt lgkmcnt(0)
	v_mfma_f32_16x16x32_bf16 v[62:65], v[140:143], v[184:187], v[62:65]
	v_mfma_f32_16x16x32_bf16 v[58:61], v[156:159], v[184:187], v[58:61]
	v_mfma_f32_16x16x32_bf16 v[46:49], v[140:143], v[196:199], v[46:49]
	v_mfma_f32_16x16x32_bf16 v[42:45], v[156:159], v[196:199], v[42:45]
	v_mfma_f32_16x16x32_bf16 v[30:33], v[140:143], v[214:217], v[30:33]
	v_mfma_f32_16x16x32_bf16 v[26:29], v[156:159], v[214:217], v[26:29]
	v_mfma_f32_16x16x32_bf16 v[14:17], v[140:143], v[222:225], v[14:17]
	v_mfma_f32_16x16x32_bf16 v[10:13], v[156:159], v[222:225], v[10:13]
	v_mfma_f32_16x16x32_bf16 v[62:65], v[152:155], v[188:191], v[62:65]
	v_mfma_f32_16x16x32_bf16 v[58:61], v[160:163], v[188:191], v[58:61]
	v_mfma_f32_16x16x32_bf16 v[46:49], v[152:155], v[210:213], v[46:49]
	v_mfma_f32_16x16x32_bf16 v[42:45], v[160:163], v[210:213], v[42:45]
	v_mfma_f32_16x16x32_bf16 v[30:33], v[152:155], v[218:221], v[30:33]
	v_mfma_f32_16x16x32_bf16 v[26:29], v[160:163], v[218:221], v[26:29]
	v_mfma_f32_16x16x32_bf16 v[14:17], v[152:155], v[226:229], v[14:17]
	v_mfma_f32_16x16x32_bf16 v[10:13], v[160:163], v[226:229], v[10:13]
	s_setprio 0
	s_setprio 1
	v_mfma_f32_16x16x32_bf16 v[54:57], v[164:167], v[184:187], v[54:57]
	v_mfma_f32_16x16x32_bf16 v[50:53], v[172:175], v[184:187], v[50:53]
	v_mfma_f32_16x16x32_bf16 v[38:41], v[164:167], v[196:199], v[38:41]
	v_mfma_f32_16x16x32_bf16 v[34:37], v[172:175], v[196:199], v[34:37]
	v_mfma_f32_16x16x32_bf16 v[22:25], v[164:167], v[214:217], v[22:25]
	v_mfma_f32_16x16x32_bf16 v[18:21], v[172:175], v[214:217], v[18:21]
	v_mfma_f32_16x16x32_bf16 v[6:9], v[164:167], v[222:225], v[6:9]
	v_mfma_f32_16x16x32_bf16 v[2:5], v[172:175], v[222:225], v[2:5]
	v_mfma_f32_16x16x32_bf16 v[54:57], v[168:171], v[188:191], v[54:57]
	v_mfma_f32_16x16x32_bf16 v[50:53], v[176:179], v[188:191], v[50:53]
	v_mfma_f32_16x16x32_bf16 v[38:41], v[168:171], v[210:213], v[38:41]
	v_mfma_f32_16x16x32_bf16 v[34:37], v[176:179], v[210:213], v[34:37]
	v_mfma_f32_16x16x32_bf16 v[22:25], v[168:171], v[218:221], v[22:25]
	v_mfma_f32_16x16x32_bf16 v[18:21], v[176:179], v[218:221], v[18:21]
	v_mfma_f32_16x16x32_bf16 v[6:9], v[168:171], v[226:229], v[6:9]
	v_mfma_f32_16x16x32_bf16 v[2:5], v[176:179], v[226:229], v[2:5]
	s_setprio 0
	s_barrier
	s_add_i32 s25, 0, 0x18000
	v_add_u32_e32 v151, s25, v147
	s_add_i32 s26, 0, 0x1c000
	ds_read_b128 v[140:143], v151
	ds_read_b128 v[152:155], v151 offset:1024
	ds_read_b128 v[156:159], v151 offset:2048
	ds_read_b128 v[160:163], v151 offset:3072
	v_add_u32_e32 v151, s26, v147
	ds_read_b128 v[164:167], v151
	ds_read_b128 v[168:171], v151 offset:1024
	ds_read_b128 v[172:175], v151 offset:2048
	ds_read_b128 v[176:179], v151 offset:3072
	s_add_u32 s36, s36, 0x40000
	s_addc_u32 s37, s37, 0
	s_mov_b32 m0, s49
	v_lshl_add_u64 v[230:231], s[36:37], 0, v[134:135]
	ds_read_b128 v[184:187], v150 offset:32768
	ds_read_b128 v[188:191], v150 offset:33792
	ds_read_b128 v[196:199], v150 offset:34816
	ds_read_b128 v[210:213], v150 offset:35840
	ds_read_b128 v[214:217], v150 offset:36864
	ds_read_b128 v[218:221], v150 offset:37888
	ds_read_b128 v[222:225], v150 offset:38912
	ds_read_b128 v[226:229], v150 offset:39936
	global_load_lds_dwordx4 v[230:231], off
	v_lshl_add_u64 v[230:231], s[36:37], 0, v[132:133]
	s_mov_b32 m0, s50
	s_nop 0
	global_load_lds_dwordx4 v[230:231], off
	s_waitcnt vmcnt(8)
	s_waitcnt lgkmcnt(0)
	s_barrier
	s_setprio 1
	s_waitcnt lgkmcnt(0)
	v_mfma_f32_16x16x32_bf16 v[126:129], v[140:143], v[184:187], v[126:129]
	v_mfma_f32_16x16x32_bf16 v[122:125], v[156:159], v[184:187], v[122:125]
	v_mfma_f32_16x16x32_bf16 v[110:113], v[140:143], v[196:199], v[110:113]
	v_mfma_f32_16x16x32_bf16 v[106:109], v[156:159], v[196:199], v[106:109]
	v_mfma_f32_16x16x32_bf16 v[94:97], v[140:143], v[214:217], v[94:97]
	v_mfma_f32_16x16x32_bf16 v[90:93], v[156:159], v[214:217], v[90:93]
	v_mfma_f32_16x16x32_bf16 v[78:81], v[140:143], v[222:225], v[78:81]
	v_mfma_f32_16x16x32_bf16 v[74:77], v[156:159], v[222:225], v[74:77]
	v_mfma_f32_16x16x32_bf16 v[126:129], v[152:155], v[188:191], v[126:129]
	v_mfma_f32_16x16x32_bf16 v[122:125], v[160:163], v[188:191], v[122:125]
	v_mfma_f32_16x16x32_bf16 v[110:113], v[152:155], v[210:213], v[110:113]
	v_mfma_f32_16x16x32_bf16 v[106:109], v[160:163], v[210:213], v[106:109]
	v_mfma_f32_16x16x32_bf16 v[94:97], v[152:155], v[218:221], v[94:97]
	v_mfma_f32_16x16x32_bf16 v[90:93], v[160:163], v[218:221], v[90:93]
	v_mfma_f32_16x16x32_bf16 v[78:81], v[152:155], v[226:229], v[78:81]
	v_mfma_f32_16x16x32_bf16 v[74:77], v[160:163], v[226:229], v[74:77]
	s_setprio 0
	s_setprio 1
	v_mfma_f32_16x16x32_bf16 v[118:121], v[164:167], v[184:187], v[118:121]
	v_mfma_f32_16x16x32_bf16 v[114:117], v[172:175], v[184:187], v[114:117]
	v_mfma_f32_16x16x32_bf16 v[102:105], v[164:167], v[196:199], v[102:105]
	v_mfma_f32_16x16x32_bf16 v[98:101], v[172:175], v[196:199], v[98:101]
	v_mfma_f32_16x16x32_bf16 v[86:89], v[164:167], v[214:217], v[86:89]
	v_mfma_f32_16x16x32_bf16 v[82:85], v[172:175], v[214:217], v[82:85]
	v_mfma_f32_16x16x32_bf16 v[70:73], v[164:167], v[222:225], v[70:73]
	v_mfma_f32_16x16x32_bf16 v[66:69], v[172:175], v[222:225], v[66:69]
	v_mfma_f32_16x16x32_bf16 v[118:121], v[168:171], v[188:191], v[118:121]
	v_mfma_f32_16x16x32_bf16 v[114:117], v[176:179], v[188:191], v[114:117]
	v_mfma_f32_16x16x32_bf16 v[102:105], v[168:171], v[210:213], v[102:105]
	v_mfma_f32_16x16x32_bf16 v[98:101], v[176:179], v[210:213], v[98:101]
	v_mfma_f32_16x16x32_bf16 v[86:89], v[168:171], v[218:221], v[86:89]
	v_mfma_f32_16x16x32_bf16 v[82:85], v[176:179], v[218:221], v[82:85]
	v_mfma_f32_16x16x32_bf16 v[70:73], v[168:171], v[226:229], v[70:73]
	v_mfma_f32_16x16x32_bf16 v[66:69], v[176:179], v[226:229], v[66:69]
	s_setprio 0
	s_barrier
	s_add_i32 s25, s25, s17
	v_lshl_add_u64 v[144:145], v[144:145], 0, s[22:23]
	s_mov_b32 m0, s25
	ds_read_b128 v[184:187], v150 offset:49152
	ds_read_b128 v[188:191], v150 offset:50176
	ds_read_b128 v[196:199], v150 offset:51200
	ds_read_b128 v[210:213], v150 offset:52224
	ds_read_b128 v[214:217], v150 offset:53248
	ds_read_b128 v[218:221], v150 offset:54272
	ds_read_b128 v[222:225], v150 offset:55296
	ds_read_b128 v[226:229], v150 offset:56320
	global_load_lds_dwordx4 v[144:145], off
	s_add_i32 m0, s25, 0x2000
	s_add_u32 s30, s30, 0x40080
	v_lshl_add_u64 v[144:145], v[180:181], 0, s[22:23]
	s_addc_u32 s31, s31, 0
	s_add_i32 s25, s26, s17
	global_load_lds_dwordx4 v[144:145], off
	v_lshl_add_u64 v[144:145], s[30:31], 0, v[0:1]
	s_mov_b32 m0, s25
	s_nop 0
	global_load_lds_dwordx4 v[144:145], off
	v_lshl_add_u64 v[144:145], s[30:31], 0, v[130:131]
	s_add_i32 m0, s25, 0x2000
	s_nop 0
	global_load_lds_dwordx4 v[144:145], off
	v_lshl_add_u64 v[144:145], v[192:193], 0, s[22:23]
	s_mov_b32 m0, s54
	s_nop 0
	global_load_lds_dwordx4 v[144:145], off
	v_lshl_add_u64 v[144:145], v[202:203], 0, s[22:23]
	s_mov_b32 m0, s55
	s_nop 0
	global_load_lds_dwordx4 v[144:145], off
	s_waitcnt vmcnt(8)
	s_waitcnt lgkmcnt(0)
	s_barrier
	s_setprio 1
	s_waitcnt lgkmcnt(0)
	v_mfma_f32_16x16x32_bf16 v[62:65], v[140:143], v[184:187], v[62:65]
	v_mfma_f32_16x16x32_bf16 v[58:61], v[156:159], v[184:187], v[58:61]
	v_mfma_f32_16x16x32_bf16 v[46:49], v[140:143], v[196:199], v[46:49]
	v_mfma_f32_16x16x32_bf16 v[42:45], v[156:159], v[196:199], v[42:45]
	v_mfma_f32_16x16x32_bf16 v[30:33], v[140:143], v[214:217], v[30:33]
	v_mfma_f32_16x16x32_bf16 v[26:29], v[156:159], v[214:217], v[26:29]
	v_mfma_f32_16x16x32_bf16 v[14:17], v[140:143], v[222:225], v[14:17]
	v_mfma_f32_16x16x32_bf16 v[10:13], v[156:159], v[222:225], v[10:13]
	v_mfma_f32_16x16x32_bf16 v[62:65], v[152:155], v[188:191], v[62:65]
	v_mfma_f32_16x16x32_bf16 v[58:61], v[160:163], v[188:191], v[58:61]
	v_mfma_f32_16x16x32_bf16 v[46:49], v[152:155], v[210:213], v[46:49]
	v_mfma_f32_16x16x32_bf16 v[42:45], v[160:163], v[210:213], v[42:45]
	v_mfma_f32_16x16x32_bf16 v[30:33], v[152:155], v[218:221], v[30:33]
	v_mfma_f32_16x16x32_bf16 v[26:29], v[160:163], v[218:221], v[26:29]
	v_mfma_f32_16x16x32_bf16 v[14:17], v[152:155], v[226:229], v[14:17]
	v_mfma_f32_16x16x32_bf16 v[10:13], v[160:163], v[226:229], v[10:13]
	s_setprio 0
	s_setprio 1
	v_mfma_f32_16x16x32_bf16 v[54:57], v[164:167], v[184:187], v[54:57]
	v_mfma_f32_16x16x32_bf16 v[50:53], v[172:175], v[184:187], v[50:53]
	v_mfma_f32_16x16x32_bf16 v[38:41], v[164:167], v[196:199], v[38:41]
	v_mfma_f32_16x16x32_bf16 v[34:37], v[172:175], v[196:199], v[34:37]
	v_mfma_f32_16x16x32_bf16 v[22:25], v[164:167], v[214:217], v[22:25]
	v_mfma_f32_16x16x32_bf16 v[18:21], v[172:175], v[214:217], v[18:21]
	v_mfma_f32_16x16x32_bf16 v[6:9], v[164:167], v[222:225], v[6:9]
	v_mfma_f32_16x16x32_bf16 v[2:5], v[172:175], v[222:225], v[2:5]
	v_mfma_f32_16x16x32_bf16 v[54:57], v[168:171], v[188:191], v[54:57]
	v_mfma_f32_16x16x32_bf16 v[50:53], v[176:179], v[188:191], v[50:53]
	v_mfma_f32_16x16x32_bf16 v[38:41], v[168:171], v[210:213], v[38:41]
	v_mfma_f32_16x16x32_bf16 v[34:37], v[176:179], v[210:213], v[34:37]
	v_mfma_f32_16x16x32_bf16 v[22:25], v[168:171], v[218:221], v[22:25]
	v_mfma_f32_16x16x32_bf16 v[18:21], v[176:179], v[218:221], v[18:21]
	v_mfma_f32_16x16x32_bf16 v[6:9], v[168:171], v[226:229], v[6:9]
	v_mfma_f32_16x16x32_bf16 v[2:5], v[176:179], v[226:229], v[2:5]
	s_setprio 0
	s_add_i32 s24, s24, 2
	s_add_u32 s12, s12, 0x100
	s_addc_u32 s13, s13, 0
	s_add_u32 s19, s19, 0x100
	s_addc_u32 s21, s21, 0
	s_cmp_gt_u32 s24, 13
	s_cbranch_scc1 .Lrot_exit_5
	s_add_u32 s25, s12, 0xfffc0080
	s_addc_u32 s26, s13, -1
	s_add_i32 s28, 0, 0x10000
	s_cmp_eq_u32 s24, 12
	s_cselect_b32 s37, s3, s26
	s_cselect_b32 s36, s16, s25
	v_add_u32_e32 v144, s28, v147
	s_cselect_b32 s31, s15, s21
	s_cselect_b32 s30, s18, s19
	s_add_i32 s25, 0, 0x14000
	s_barrier
	s_branch .Lrot_body_5
